# changed: GEMM K-loops use one static priority raise for the trailing wave group instead of per-MFMA-block s_setprio toggles
# speedup vs baseline: 1.0151x; 1.0054x over previous
.LBB0_2:
	s_load_dword s33, s[0:1], 0xb0
	v_and_b32_e32 v195, 0x3ff, v0
	v_readfirstlane_b32 s32, v195
	v_mov_b32_e32 v1, v195
	s_nop 0
	v_cmp_gt_i32_e32 vcc, 32, v1
	s_and_saveexec_b64 s[4:5], vcc
	s_cbranch_execz .LBB0_4
	v_mov_b32_e32 v1, v195
	v_mov_b32_e32 v2, 0
	v_lshl_add_u32 v1, v1, 2, 0
	v_add_u32_e32 v1, 0x20000, v1
	ds_write_b32 v1, v2

.LBB0_213:
	s_ashr_i32 s45, s44, 31
	s_lshl_b64 s[2:3], s[44:45], 19
	s_add_u32 s46, s18, s2
	s_addc_u32 s47, s19, s3
	s_and_b64 s[2:3], s[38:39], exec
	s_cselect_b32 s2, s47, s53
	s_cselect_b32 s3, s46, s52
	s_ashr_i32 s43, s42, 31
	s_lshl_b64 s[24:25], s[42:43], 19
	s_add_u32 s48, s97, s24
	v_readlane_b32 s13, v255, 8
	s_addc_u32 s49, s13, s25
	s_and_b64 s[24:25], s[38:39], exec
	s_cselect_b32 s13, s49, s71
	s_cselect_b32 s16, s48, s70
	s_add_u32 s30, s52, 0x40080
	s_addc_u32 s31, s53, 0
	s_add_u32 s24, s70, 0x100
	s_addc_u32 s25, s71, 0
	s_mov_b32 s26, -2
	v_mov_b64_e32 v[2:3], 0
	v_mov_b64_e32 v[4:5], 0
	v_mov_b64_e32 v[6:7], 0
	v_mov_b64_e32 v[8:9], 0
	v_mov_b64_e32 v[10:11], 0
	v_mov_b64_e32 v[12:13], 0
	v_mov_b64_e32 v[14:15], 0
	v_mov_b64_e32 v[16:17], 0
	v_mov_b64_e32 v[18:19], 0
	v_mov_b64_e32 v[20:21], 0
	v_mov_b64_e32 v[22:23], 0
	v_mov_b64_e32 v[24:25], 0
	v_mov_b64_e32 v[26:27], 0
	v_mov_b64_e32 v[28:29], 0
	v_mov_b64_e32 v[30:31], 0
	v_mov_b64_e32 v[32:33], 0
	v_mov_b64_e32 v[34:35], 0
	v_mov_b64_e32 v[36:37], 0
	v_mov_b64_e32 v[38:39], 0
	v_mov_b64_e32 v[40:41], 0
	v_mov_b64_e32 v[42:43], 0
	v_mov_b64_e32 v[44:45], 0
	v_mov_b64_e32 v[46:47], 0
	v_mov_b64_e32 v[48:49], 0
	v_mov_b64_e32 v[50:51], 0
	v_mov_b64_e32 v[52:53], 0
	v_mov_b64_e32 v[54:55], 0
	v_mov_b64_e32 v[56:57], 0
	v_mov_b64_e32 v[58:59], 0
	v_mov_b64_e32 v[60:61], 0
	v_mov_b64_e32 v[62:63], 0
	v_mov_b64_e32 v[64:65], 0
	v_mov_b64_e32 v[66:67], 0
	v_mov_b64_e32 v[68:69], 0
	v_mov_b64_e32 v[70:71], 0
	v_mov_b64_e32 v[72:73], 0
	v_mov_b64_e32 v[74:75], 0
	v_mov_b64_e32 v[76:77], 0
	v_mov_b64_e32 v[78:79], 0
	v_mov_b64_e32 v[80:81], 0
	v_mov_b64_e32 v[82:83], 0
	v_mov_b64_e32 v[84:85], 0
	v_mov_b64_e32 v[86:87], 0
	v_mov_b64_e32 v[88:89], 0
	v_mov_b64_e32 v[90:91], 0
	v_mov_b64_e32 v[92:93], 0
	v_mov_b64_e32 v[94:95], 0
	v_mov_b64_e32 v[96:97], 0
	v_mov_b64_e32 v[98:99], 0
	v_mov_b64_e32 v[100:101], 0
	v_mov_b64_e32 v[102:103], 0
	v_mov_b64_e32 v[104:105], 0
	v_mov_b64_e32 v[106:107], 0
	v_mov_b64_e32 v[108:109], 0
	v_mov_b64_e32 v[110:111], 0
	v_mov_b64_e32 v[112:113], 0
	v_mov_b64_e32 v[114:115], 0
	v_mov_b64_e32 v[116:117], 0
	v_mov_b64_e32 v[118:119], 0
	v_mov_b64_e32 v[120:121], 0
	v_mov_b64_e32 v[122:123], 0
	v_mov_b64_e32 v[124:125], 0
	v_mov_b64_e32 v[126:127], 0
	v_mov_b64_e32 v[128:129], 0
	s_cmp_lt_u32 s32, 0x100
	s_cbranch_scc1 .Lsprio_0
	s_setprio 1
.Lsprio_0:
.LBB0_214:
	s_add_u32 s28, s30, 0xfffc0080
	s_addc_u32 s36, s31, -1
	s_add_i32 s43, 0, 0x10000
	s_cmp_eq_u32 s26, 12
	s_cselect_b32 s53, s2, s36
	s_cselect_b32 s52, s3, s28
	v_add_u32_e32 v157, s43, v153
	s_cselect_b32 s37, s13, s25
	s_cselect_b32 s36, s16, s24
	s_add_i32 s28, 0, 0x14000
	ds_read_b128 v[130:133], v157
	ds_read_b128 v[148:151], v157 offset:1024
	ds_read_b128 v[158:161], v157 offset:2048
	ds_read_b128 v[162:165], v157 offset:3072
	v_add_u32_e32 v157, s28, v153
	ds_read_b128 v[166:169], v157
	ds_read_b128 v[170:173], v157 offset:1024
	ds_read_b128 v[174:177], v157 offset:2048
	ds_read_b128 v[178:181], v157 offset:3072
	v_lshl_add_u64 v[192:193], s[30:31], 0, v[144:145]
	s_add_i32 m0, s75, 0xc000
	ds_read_b128 v[184:187], v156
	ds_read_b128 v[188:191], v156 offset:1024
	ds_read_b128 v[196:199], v156 offset:2048
	ds_read_b128 v[210:213], v156 offset:3072
	ds_read_b128 v[214:217], v156 offset:4096
	ds_read_b128 v[218:221], v156 offset:5120
	ds_read_b128 v[222:225], v156 offset:6144
	ds_read_b128 v[226:229], v156 offset:7168
	global_load_lds_dwordx4 v[192:193], off
	v_lshl_add_u64 v[192:193], s[30:31], 0, v[146:147]
	s_add_i32 m0, s75, 0xe000
	s_nop 0
	global_load_lds_dwordx4 v[192:193], off
	s_waitcnt vmcnt(8)
	s_waitcnt lgkmcnt(0)
	s_barrier
	s_waitcnt lgkmcnt(0)
	v_mfma_f32_16x16x32_bf16 v[126:129], v[130:133], v[184:187], v[126:129]
	v_mfma_f32_16x16x32_bf16 v[122:125], v[158:161], v[184:187], v[122:125]
	v_mfma_f32_16x16x32_bf16 v[110:113], v[130:133], v[196:199], v[110:113]
	v_mfma_f32_16x16x32_bf16 v[106:109], v[158:161], v[196:199], v[106:109]
	v_mfma_f32_16x16x32_bf16 v[94:97], v[130:133], v[214:217], v[94:97]
	v_mfma_f32_16x16x32_bf16 v[90:93], v[158:161], v[214:217], v[90:93]
	v_mfma_f32_16x16x32_bf16 v[78:81], v[130:133], v[222:225], v[78:81]
	v_mfma_f32_16x16x32_bf16 v[74:77], v[158:161], v[222:225], v[74:77]
	v_mfma_f32_16x16x32_bf16 v[126:129], v[148:151], v[188:191], v[126:129]
	v_mfma_f32_16x16x32_bf16 v[122:125], v[162:165], v[188:191], v[122:125]
	v_mfma_f32_16x16x32_bf16 v[110:113], v[148:151], v[210:213], v[110:113]
	v_mfma_f32_16x16x32_bf16 v[106:109], v[162:165], v[210:213], v[106:109]
	v_mfma_f32_16x16x32_bf16 v[94:97], v[148:151], v[218:221], v[94:97]
	v_mfma_f32_16x16x32_bf16 v[90:93], v[162:165], v[218:221], v[90:93]
	v_mfma_f32_16x16x32_bf16 v[78:81], v[148:151], v[226:229], v[78:81]
	v_mfma_f32_16x16x32_bf16 v[74:77], v[162:165], v[226:229], v[74:77]
	v_mfma_f32_16x16x32_bf16 v[118:121], v[166:169], v[184:187], v[118:121]
	v_mfma_f32_16x16x32_bf16 v[114:117], v[174:177], v[184:187], v[114:117]
	v_mfma_f32_16x16x32_bf16 v[102:105], v[166:169], v[196:199], v[102:105]
	v_mfma_f32_16x16x32_bf16 v[98:101], v[174:177], v[196:199], v[98:101]
	v_mfma_f32_16x16x32_bf16 v[86:89], v[166:169], v[214:217], v[86:89]
	v_mfma_f32_16x16x32_bf16 v[82:85], v[174:177], v[214:217], v[82:85]
	v_mfma_f32_16x16x32_bf16 v[70:73], v[166:169], v[222:225], v[70:73]
	v_mfma_f32_16x16x32_bf16 v[66:69], v[174:177], v[222:225], v[66:69]
	v_mfma_f32_16x16x32_bf16 v[118:121], v[170:173], v[188:191], v[118:121]
	v_mfma_f32_16x16x32_bf16 v[114:117], v[178:181], v[188:191], v[114:117]
	v_mfma_f32_16x16x32_bf16 v[102:105], v[170:173], v[210:213], v[102:105]
	v_mfma_f32_16x16x32_bf16 v[98:101], v[178:181], v[210:213], v[98:101]
	v_mfma_f32_16x16x32_bf16 v[86:89], v[170:173], v[218:221], v[86:89]
	v_mfma_f32_16x16x32_bf16 v[82:85], v[178:181], v[218:221], v[82:85]
	v_mfma_f32_16x16x32_bf16 v[70:73], v[170:173], v[226:229], v[70:73]
	v_mfma_f32_16x16x32_bf16 v[66:69], v[178:181], v[226:229], v[66:69]
	s_barrier
	s_add_i32 s43, s43, s17
	v_lshl_add_u64 v[192:193], s[36:37], 0, v[0:1]
	s_mov_b32 m0, s43
	ds_read_b128 v[184:187], v156 offset:16384
	ds_read_b128 v[188:191], v156 offset:17408
	ds_read_b128 v[196:199], v156 offset:18432
	ds_read_b128 v[210:213], v156 offset:19456
	ds_read_b128 v[214:217], v156 offset:20480
	ds_read_b128 v[218:221], v156 offset:21504
	ds_read_b128 v[222:225], v156 offset:22528
	ds_read_b128 v[226:229], v156 offset:23552
	global_load_lds_dwordx4 v[192:193], off
	s_add_i32 m0, s43, 0x2000
	s_add_u32 s70, s36, 0x40000
	v_lshl_add_u64 v[202:203], s[36:37], 0, v[134:135]
	s_addc_u32 s71, s37, 0
	s_add_i32 s28, s28, s17
	global_load_lds_dwordx4 v[202:203], off
	v_lshl_add_u64 v[230:231], s[70:71], 0, v[0:1]
	s_mov_b32 m0, s28
	v_lshl_add_u64 v[232:233], s[52:53], 0, v[136:137]
	global_load_lds_dwordx4 v[230:231], off
	v_lshl_add_u64 v[230:231], s[70:71], 0, v[134:135]
	s_add_i32 m0, s28, 0x2000
	s_nop 0
	global_load_lds_dwordx4 v[230:231], off
	v_lshl_add_u64 v[230:231], s[52:53], 0, v[138:139]
	s_mov_b32 m0, s75
	s_nop 0
	global_load_lds_dwordx4 v[230:231], off
	s_mov_b32 m0, s58
	s_nop 0
	global_load_lds_dwordx4 v[232:233], off
	s_waitcnt vmcnt(8)
	s_waitcnt lgkmcnt(0)
	s_barrier
	s_waitcnt lgkmcnt(0)
	v_mfma_f32_16x16x32_bf16 v[62:65], v[130:133], v[184:187], v[62:65]
	v_mfma_f32_16x16x32_bf16 v[58:61], v[158:161], v[184:187], v[58:61]
	v_mfma_f32_16x16x32_bf16 v[46:49], v[130:133], v[196:199], v[46:49]
	v_mfma_f32_16x16x32_bf16 v[42:45], v[158:161], v[196:199], v[42:45]
	v_mfma_f32_16x16x32_bf16 v[30:33], v[130:133], v[214:217], v[30:33]
	v_mfma_f32_16x16x32_bf16 v[26:29], v[158:161], v[214:217], v[26:29]
	v_mfma_f32_16x16x32_bf16 v[14:17], v[130:133], v[222:225], v[14:17]
	v_mfma_f32_16x16x32_bf16 v[10:13], v[158:161], v[222:225], v[10:13]
	v_mfma_f32_16x16x32_bf16 v[62:65], v[148:151], v[188:191], v[62:65]
	v_mfma_f32_16x16x32_bf16 v[58:61], v[162:165], v[188:191], v[58:61]
	v_mfma_f32_16x16x32_bf16 v[46:49], v[148:151], v[210:213], v[46:49]
	v_mfma_f32_16x16x32_bf16 v[42:45], v[162:165], v[210:213], v[42:45]
	v_mfma_f32_16x16x32_bf16 v[30:33], v[148:151], v[218:221], v[30:33]
	v_mfma_f32_16x16x32_bf16 v[26:29], v[162:165], v[218:221], v[26:29]
	v_mfma_f32_16x16x32_bf16 v[14:17], v[148:151], v[226:229], v[14:17]
	v_mfma_f32_16x16x32_bf16 v[10:13], v[162:165], v[226:229], v[10:13]
	v_mfma_f32_16x16x32_bf16 v[54:57], v[166:169], v[184:187], v[54:57]
	v_mfma_f32_16x16x32_bf16 v[50:53], v[174:177], v[184:187], v[50:53]
	v_mfma_f32_16x16x32_bf16 v[38:41], v[166:169], v[196:199], v[38:41]
	v_mfma_f32_16x16x32_bf16 v[34:37], v[174:177], v[196:199], v[34:37]
	v_mfma_f32_16x16x32_bf16 v[22:25], v[166:169], v[214:217], v[22:25]
	v_mfma_f32_16x16x32_bf16 v[18:21], v[174:177], v[214:217], v[18:21]
	v_mfma_f32_16x16x32_bf16 v[6:9], v[166:169], v[222:225], v[6:9]
	v_mfma_f32_16x16x32_bf16 v[2:5], v[174:177], v[222:225], v[2:5]
	v_mfma_f32_16x16x32_bf16 v[54:57], v[170:173], v[188:191], v[54:57]
	v_mfma_f32_16x16x32_bf16 v[50:53], v[178:181], v[188:191], v[50:53]
	v_mfma_f32_16x16x32_bf16 v[38:41], v[170:173], v[210:213], v[38:41]
	v_mfma_f32_16x16x32_bf16 v[34:37], v[178:181], v[210:213], v[34:37]
	v_mfma_f32_16x16x32_bf16 v[22:25], v[170:173], v[218:221], v[22:25]
	v_mfma_f32_16x16x32_bf16 v[18:21], v[178:181], v[218:221], v[18:21]
	v_mfma_f32_16x16x32_bf16 v[6:9], v[170:173], v[226:229], v[6:9]
	v_mfma_f32_16x16x32_bf16 v[2:5], v[178:181], v[226:229], v[2:5]
	s_barrier
	s_add_i32 s28, 0, 0x18000
	v_add_u32_e32 v157, s28, v153
	s_add_i32 s43, 0, 0x1c000
	ds_read_b128 v[130:133], v157
	ds_read_b128 v[148:151], v157 offset:1024
	ds_read_b128 v[158:161], v157 offset:2048
	ds_read_b128 v[162:165], v157 offset:3072
	v_add_u32_e32 v157, s43, v153
	ds_read_b128 v[166:169], v157
	ds_read_b128 v[170:173], v157 offset:1024
	ds_read_b128 v[174:177], v157 offset:2048
	ds_read_b128 v[178:181], v157 offset:3072
	s_add_u32 s52, s52, 0x40000
	s_addc_u32 s53, s53, 0
	s_mov_b32 m0, s59
	v_lshl_add_u64 v[234:235], s[52:53], 0, v[138:139]
	ds_read_b128 v[184:187], v156 offset:32768
	ds_read_b128 v[188:191], v156 offset:33792
	ds_read_b128 v[196:199], v156 offset:34816
	ds_read_b128 v[210:213], v156 offset:35840
	ds_read_b128 v[214:217], v156 offset:36864
	ds_read_b128 v[218:221], v156 offset:37888
	ds_read_b128 v[222:225], v156 offset:38912
	ds_read_b128 v[226:229], v156 offset:39936
	global_load_lds_dwordx4 v[234:235], off
	v_lshl_add_u64 v[234:235], s[52:53], 0, v[136:137]
	s_mov_b32 m0, s60
	s_nop 0
	global_load_lds_dwordx4 v[234:235], off
	s_waitcnt vmcnt(8)
	s_waitcnt lgkmcnt(0)
	s_barrier
	s_waitcnt lgkmcnt(0)
	v_mfma_f32_16x16x32_bf16 v[126:129], v[130:133], v[184:187], v[126:129]
	v_mfma_f32_16x16x32_bf16 v[122:125], v[158:161], v[184:187], v[122:125]
	v_mfma_f32_16x16x32_bf16 v[110:113], v[130:133], v[196:199], v[110:113]
	v_mfma_f32_16x16x32_bf16 v[106:109], v[158:161], v[196:199], v[106:109]
	v_mfma_f32_16x16x32_bf16 v[94:97], v[130:133], v[214:217], v[94:97]
	v_mfma_f32_16x16x32_bf16 v[90:93], v[158:161], v[214:217], v[90:93]
	v_mfma_f32_16x16x32_bf16 v[78:81], v[130:133], v[222:225], v[78:81]
	v_mfma_f32_16x16x32_bf16 v[74:77], v[158:161], v[222:225], v[74:77]
	v_mfma_f32_16x16x32_bf16 v[126:129], v[148:151], v[188:191], v[126:129]
	v_mfma_f32_16x16x32_bf16 v[122:125], v[162:165], v[188:191], v[122:125]
	v_mfma_f32_16x16x32_bf16 v[110:113], v[148:151], v[210:213], v[110:113]
	v_mfma_f32_16x16x32_bf16 v[106:109], v[162:165], v[210:213], v[106:109]
	v_mfma_f32_16x16x32_bf16 v[94:97], v[148:151], v[218:221], v[94:97]
	v_mfma_f32_16x16x32_bf16 v[90:93], v[162:165], v[218:221], v[90:93]
	v_mfma_f32_16x16x32_bf16 v[78:81], v[148:151], v[226:229], v[78:81]
	v_mfma_f32_16x16x32_bf16 v[74:77], v[162:165], v[226:229], v[74:77]
	v_mfma_f32_16x16x32_bf16 v[118:121], v[166:169], v[184:187], v[118:121]
	v_mfma_f32_16x16x32_bf16 v[114:117], v[174:177], v[184:187], v[114:117]
	v_mfma_f32_16x16x32_bf16 v[102:105], v[166:169], v[196:199], v[102:105]
	v_mfma_f32_16x16x32_bf16 v[98:101], v[174:177], v[196:199], v[98:101]
	v_mfma_f32_16x16x32_bf16 v[86:89], v[166:169], v[214:217], v[86:89]
	v_mfma_f32_16x16x32_bf16 v[82:85], v[174:177], v[214:217], v[82:85]
	v_mfma_f32_16x16x32_bf16 v[70:73], v[166:169], v[222:225], v[70:73]
	v_mfma_f32_16x16x32_bf16 v[66:69], v[174:177], v[222:225], v[66:69]
	v_mfma_f32_16x16x32_bf16 v[118:121], v[170:173], v[188:191], v[118:121]
	v_mfma_f32_16x16x32_bf16 v[114:117], v[178:181], v[188:191], v[114:117]
	v_mfma_f32_16x16x32_bf16 v[102:105], v[170:173], v[210:213], v[102:105]
	v_mfma_f32_16x16x32_bf16 v[98:101], v[178:181], v[210:213], v[98:101]
	v_mfma_f32_16x16x32_bf16 v[86:89], v[170:173], v[218:221], v[86:89]
	v_mfma_f32_16x16x32_bf16 v[82:85], v[178:181], v[218:221], v[82:85]
	v_mfma_f32_16x16x32_bf16 v[70:73], v[170:173], v[226:229], v[70:73]
	v_mfma_f32_16x16x32_bf16 v[66:69], v[178:181], v[226:229], v[66:69]
	s_barrier
	s_add_i32 s28, s28, s17
	v_lshl_add_u64 v[192:193], v[192:193], 0, s[22:23]
	s_mov_b32 m0, s28
	ds_read_b128 v[184:187], v156 offset:49152
	ds_read_b128 v[188:191], v156 offset:50176
	ds_read_b128 v[196:199], v156 offset:51200
	ds_read_b128 v[210:213], v156 offset:52224
	ds_read_b128 v[214:217], v156 offset:53248
	ds_read_b128 v[218:221], v156 offset:54272
	ds_read_b128 v[222:225], v156 offset:55296
	ds_read_b128 v[226:229], v156 offset:56320
	global_load_lds_dwordx4 v[192:193], off
	s_add_i32 m0, s28, 0x2000
	s_add_u32 s36, s36, 0x40080
	v_lshl_add_u64 v[192:193], v[202:203], 0, s[22:23]
	s_addc_u32 s37, s37, 0
	s_add_i32 s28, s43, s17
	global_load_lds_dwordx4 v[192:193], off
	v_lshl_add_u64 v[192:193], s[36:37], 0, v[0:1]
	s_mov_b32 m0, s28
	s_nop 0
	global_load_lds_dwordx4 v[192:193], off
	v_lshl_add_u64 v[192:193], s[36:37], 0, v[134:135]
	s_add_i32 m0, s28, 0x2000
	s_nop 0
	global_load_lds_dwordx4 v[192:193], off
	v_lshl_add_u64 v[192:193], v[230:231], 0, s[22:23]
	s_mov_b32 m0, s62
	s_nop 0
	global_load_lds_dwordx4 v[192:193], off
	v_lshl_add_u64 v[192:193], v[232:233], 0, s[22:23]
	s_mov_b32 m0, s63
	s_nop 0
	global_load_lds_dwordx4 v[192:193], off
	s_waitcnt vmcnt(8)
	s_waitcnt lgkmcnt(0)
	s_barrier
	s_waitcnt lgkmcnt(0)
	v_mfma_f32_16x16x32_bf16 v[62:65], v[130:133], v[184:187], v[62:65]
	v_mfma_f32_16x16x32_bf16 v[58:61], v[158:161], v[184:187], v[58:61]
	v_mfma_f32_16x16x32_bf16 v[46:49], v[130:133], v[196:199], v[46:49]
	v_mfma_f32_16x16x32_bf16 v[42:45], v[158:161], v[196:199], v[42:45]
	v_mfma_f32_16x16x32_bf16 v[30:33], v[130:133], v[214:217], v[30:33]
	v_mfma_f32_16x16x32_bf16 v[26:29], v[158:161], v[214:217], v[26:29]
	v_mfma_f32_16x16x32_bf16 v[14:17], v[130:133], v[222:225], v[14:17]
	v_mfma_f32_16x16x32_bf16 v[10:13], v[158:161], v[222:225], v[10:13]
	v_mfma_f32_16x16x32_bf16 v[62:65], v[148:151], v[188:191], v[62:65]
	v_mfma_f32_16x16x32_bf16 v[58:61], v[162:165], v[188:191], v[58:61]
	v_mfma_f32_16x16x32_bf16 v[46:49], v[148:151], v[210:213], v[46:49]
	v_mfma_f32_16x16x32_bf16 v[42:45], v[162:165], v[210:213], v[42:45]
	v_mfma_f32_16x16x32_bf16 v[30:33], v[148:151], v[218:221], v[30:33]
	v_mfma_f32_16x16x32_bf16 v[26:29], v[162:165], v[218:221], v[26:29]
	v_mfma_f32_16x16x32_bf16 v[14:17], v[148:151], v[226:229], v[14:17]
	v_mfma_f32_16x16x32_bf16 v[10:13], v[162:165], v[226:229], v[10:13]
	v_mfma_f32_16x16x32_bf16 v[54:57], v[166:169], v[184:187], v[54:57]
	v_mfma_f32_16x16x32_bf16 v[50:53], v[174:177], v[184:187], v[50:53]
	v_mfma_f32_16x16x32_bf16 v[38:41], v[166:169], v[196:199], v[38:41]
	v_mfma_f32_16x16x32_bf16 v[34:37], v[174:177], v[196:199], v[34:37]
	v_mfma_f32_16x16x32_bf16 v[22:25], v[166:169], v[214:217], v[22:25]
	v_mfma_f32_16x16x32_bf16 v[18:21], v[174:177], v[214:217], v[18:21]
	v_mfma_f32_16x16x32_bf16 v[6:9], v[166:169], v[222:225], v[6:9]
	v_mfma_f32_16x16x32_bf16 v[2:5], v[174:177], v[222:225], v[2:5]
	v_mfma_f32_16x16x32_bf16 v[54:57], v[170:173], v[188:191], v[54:57]
	v_mfma_f32_16x16x32_bf16 v[50:53], v[178:181], v[188:191], v[50:53]
	v_mfma_f32_16x16x32_bf16 v[38:41], v[170:173], v[210:213], v[38:41]
	v_mfma_f32_16x16x32_bf16 v[34:37], v[178:181], v[210:213], v[34:37]
	v_mfma_f32_16x16x32_bf16 v[22:25], v[170:173], v[218:221], v[22:25]
	v_mfma_f32_16x16x32_bf16 v[18:21], v[178:181], v[218:221], v[18:21]
	v_mfma_f32_16x16x32_bf16 v[6:9], v[170:173], v[226:229], v[6:9]
	v_mfma_f32_16x16x32_bf16 v[2:5], v[178:181], v[226:229], v[2:5]
	s_barrier
	s_add_i32 s26, s26, 2
	s_add_u32 s30, s30, 0x100
	s_addc_u32 s31, s31, 0
	s_add_u32 s24, s24, 0x100
	s_addc_u32 s25, s25, 0
	s_cmp_gt_u32 s26, 13
	s_cbranch_scc0 .LBB0_214
	s_setprio 0
	s_and_b64 vcc, exec, s[34:35]
	s_cbranch_vccz .LBB0_227
	s_barrier
	v_lshl_add_u32 v148, s12, 8, v152
	s_cmp_lt_i32 s74, s64
	s_mov_b64 s[12:13], -1
	s_cbranch_scc0 .LBB0_228

.LBB0_694:
	s_ashr_i32 s45, s44, 31
	s_lshl_b64 s[24:25], s[44:45], 19
	s_add_u32 s46, s17, s24
	s_addc_u32 s47, s18, s25
	s_and_b64 s[24:25], s[42:43], exec
	s_cselect_b32 s3, s47, s13
	s_cselect_b32 s16, s46, s12
	s_ashr_i32 s35, s34, 31
	s_lshl_b64 s[24:25], s[34:35], 19
	s_add_u32 s48, s19, s24
	s_addc_u32 s49, s29, s25
	s_and_b64 s[24:25], s[42:43], exec
	s_cselect_b32 s24, s49, s31
	s_cselect_b32 s25, s48, s30
	s_add_u32 s12, s12, 0x40080
	s_addc_u32 s13, s13, 0
	s_add_u32 s26, s30, 0x100
	s_addc_u32 s28, s31, 0
	s_mov_b32 s35, -2
	s_waitcnt vmcnt(0)
	v_mov_b64_e32 v[2:3], 0
	v_mov_b64_e32 v[4:5], 0
	v_mov_b64_e32 v[6:7], 0
	v_mov_b64_e32 v[8:9], 0
	v_mov_b64_e32 v[10:11], 0
	v_mov_b64_e32 v[12:13], 0
	v_mov_b64_e32 v[14:15], 0
	v_mov_b64_e32 v[16:17], 0
	v_mov_b64_e32 v[18:19], 0
	v_mov_b64_e32 v[20:21], 0
	v_mov_b64_e32 v[22:23], 0
	v_mov_b64_e32 v[24:25], 0
	v_mov_b64_e32 v[26:27], 0
	v_mov_b64_e32 v[28:29], 0
	v_mov_b64_e32 v[30:31], 0
	v_mov_b64_e32 v[32:33], 0
	v_mov_b64_e32 v[34:35], 0
	v_mov_b64_e32 v[36:37], 0
	v_mov_b64_e32 v[38:39], 0
	v_mov_b64_e32 v[40:41], 0
	v_mov_b64_e32 v[42:43], 0
	v_mov_b64_e32 v[44:45], 0
	v_mov_b64_e32 v[46:47], 0
	v_mov_b64_e32 v[48:49], 0
	v_mov_b64_e32 v[50:51], 0
	v_mov_b64_e32 v[52:53], 0
	v_mov_b64_e32 v[54:55], 0
	v_mov_b64_e32 v[56:57], 0
	v_mov_b64_e32 v[58:59], 0
	v_mov_b64_e32 v[60:61], 0
	v_mov_b64_e32 v[62:63], 0
	v_mov_b64_e32 v[64:65], 0
	v_mov_b64_e32 v[66:67], 0
	v_mov_b64_e32 v[68:69], 0
	v_mov_b64_e32 v[70:71], 0
	v_mov_b64_e32 v[72:73], 0
	v_mov_b64_e32 v[74:75], 0
	v_mov_b64_e32 v[76:77], 0
	v_mov_b64_e32 v[78:79], 0
	v_mov_b64_e32 v[80:81], 0
	v_mov_b64_e32 v[82:83], 0
	v_mov_b64_e32 v[84:85], 0
	v_mov_b64_e32 v[86:87], 0
	v_mov_b64_e32 v[88:89], 0
	v_mov_b64_e32 v[90:91], 0
	v_mov_b64_e32 v[92:93], 0
	v_mov_b64_e32 v[94:95], 0
	v_mov_b64_e32 v[96:97], 0
	v_mov_b64_e32 v[98:99], 0
	v_mov_b64_e32 v[100:101], 0
	v_mov_b64_e32 v[102:103], 0
	v_mov_b64_e32 v[104:105], 0
	v_mov_b64_e32 v[106:107], 0
	v_mov_b64_e32 v[108:109], 0
	v_mov_b64_e32 v[110:111], 0
	v_mov_b64_e32 v[112:113], 0
	v_mov_b64_e32 v[114:115], 0
	v_mov_b64_e32 v[116:117], 0
	v_mov_b64_e32 v[118:119], 0
	v_mov_b64_e32 v[120:121], 0
	v_mov_b64_e32 v[122:123], 0
	v_mov_b64_e32 v[124:125], 0
	v_mov_b64_e32 v[126:127], 0
	v_mov_b64_e32 v[128:129], 0
	s_cmp_lt_u32 s32, 0x100
	s_cbranch_scc1 .Lsprio_1
	s_setprio 1
.Lsprio_1:
.LBB0_695:
	s_add_u32 s30, s12, 0xfffc0080
	s_addc_u32 s31, s13, -1
	s_add_i32 s45, 0, 0x10000
	s_cmp_eq_u32 s35, 12
	s_cselect_b32 s37, s3, s31
	s_cselect_b32 s36, s16, s30
	s_cselect_b32 s31, s24, s28
	s_cselect_b32 s30, s25, s26
	s_add_i32 s59, 0, 0x14000
	v_add_u32_e32 v156, s45, v145
	v_add_u32_e32 v172, s59, v145
	ds_read_b128 v[140:143], v156
	ds_read_b128 v[148:151], v156 offset:1024
	ds_read_b128 v[152:155], v156 offset:2048
	ds_read_b128 v[156:159], v156 offset:3072
	ds_read_b128 v[160:163], v172
	ds_read_b128 v[164:167], v172 offset:1024
	ds_read_b128 v[168:171], v172 offset:2048
	ds_read_b128 v[172:175], v172 offset:3072
	v_lshl_add_u64 v[180:181], s[12:13], 0, v[136:137]
	s_add_i32 m0, s51, 0xc000
	ds_read_b128 v[176:179], v147
	ds_read_b128 v[184:187], v147 offset:1024
	ds_read_b128 v[188:191], v147 offset:2048
	ds_read_b128 v[196:199], v147 offset:3072
	ds_read_b128 v[210:213], v147 offset:4096
	ds_read_b128 v[214:217], v147 offset:5120
	ds_read_b128 v[218:221], v147 offset:6144
	ds_read_b128 v[222:225], v147 offset:7168
	global_load_lds_dwordx4 v[180:181], off
	v_lshl_add_u64 v[180:181], s[12:13], 0, v[138:139]
	s_add_i32 m0, s51, 0xe000
	s_nop 0
	global_load_lds_dwordx4 v[180:181], off
	s_waitcnt vmcnt(8)
	s_waitcnt lgkmcnt(0)
	s_barrier
	s_waitcnt lgkmcnt(0)
	v_mfma_f32_16x16x32_bf16 v[126:129], v[140:143], v[176:179], v[126:129]
	v_mfma_f32_16x16x32_bf16 v[122:125], v[152:155], v[176:179], v[122:125]
	v_mfma_f32_16x16x32_bf16 v[110:113], v[140:143], v[188:191], v[110:113]
	v_mfma_f32_16x16x32_bf16 v[106:109], v[152:155], v[188:191], v[106:109]
	v_mfma_f32_16x16x32_bf16 v[94:97], v[140:143], v[210:213], v[94:97]
	v_mfma_f32_16x16x32_bf16 v[90:93], v[152:155], v[210:213], v[90:93]
	v_mfma_f32_16x16x32_bf16 v[78:81], v[140:143], v[218:221], v[78:81]
	v_mfma_f32_16x16x32_bf16 v[74:77], v[152:155], v[218:221], v[74:77]
	v_mfma_f32_16x16x32_bf16 v[126:129], v[148:151], v[184:187], v[126:129]
	v_mfma_f32_16x16x32_bf16 v[122:125], v[156:159], v[184:187], v[122:125]
	v_mfma_f32_16x16x32_bf16 v[110:113], v[148:151], v[196:199], v[110:113]
	v_mfma_f32_16x16x32_bf16 v[106:109], v[156:159], v[196:199], v[106:109]
	v_mfma_f32_16x16x32_bf16 v[94:97], v[148:151], v[214:217], v[94:97]
	v_mfma_f32_16x16x32_bf16 v[90:93], v[156:159], v[214:217], v[90:93]
	v_mfma_f32_16x16x32_bf16 v[78:81], v[148:151], v[222:225], v[78:81]
	v_mfma_f32_16x16x32_bf16 v[74:77], v[156:159], v[222:225], v[74:77]
	v_mfma_f32_16x16x32_bf16 v[118:121], v[160:163], v[176:179], v[118:121]
	v_mfma_f32_16x16x32_bf16 v[114:117], v[168:171], v[176:179], v[114:117]
	v_mfma_f32_16x16x32_bf16 v[102:105], v[160:163], v[188:191], v[102:105]
	v_mfma_f32_16x16x32_bf16 v[98:101], v[168:171], v[188:191], v[98:101]
	v_mfma_f32_16x16x32_bf16 v[86:89], v[160:163], v[210:213], v[86:89]
	v_mfma_f32_16x16x32_bf16 v[82:85], v[168:171], v[210:213], v[82:85]
	v_mfma_f32_16x16x32_bf16 v[70:73], v[160:163], v[218:221], v[70:73]
	v_mfma_f32_16x16x32_bf16 v[66:69], v[168:171], v[218:221], v[66:69]
	v_mfma_f32_16x16x32_bf16 v[118:121], v[164:167], v[184:187], v[118:121]
	v_mfma_f32_16x16x32_bf16 v[114:117], v[172:175], v[184:187], v[114:117]
	v_mfma_f32_16x16x32_bf16 v[102:105], v[164:167], v[196:199], v[102:105]
	v_mfma_f32_16x16x32_bf16 v[98:101], v[172:175], v[196:199], v[98:101]
	v_mfma_f32_16x16x32_bf16 v[86:89], v[164:167], v[214:217], v[86:89]
	v_mfma_f32_16x16x32_bf16 v[82:85], v[172:175], v[214:217], v[82:85]
	v_mfma_f32_16x16x32_bf16 v[70:73], v[164:167], v[222:225], v[70:73]
	v_mfma_f32_16x16x32_bf16 v[66:69], v[172:175], v[222:225], v[66:69]
	s_barrier
	s_add_i32 s45, s45, s50
	v_lshl_add_u64 v[180:181], s[30:31], 0, v[0:1]
	s_mov_b32 m0, s45
	ds_read_b128 v[176:179], v147 offset:16384
	ds_read_b128 v[184:187], v147 offset:17408
	ds_read_b128 v[188:191], v147 offset:18432
	ds_read_b128 v[196:199], v147 offset:19456
	ds_read_b128 v[210:213], v147 offset:20480
	ds_read_b128 v[214:217], v147 offset:21504
	ds_read_b128 v[218:221], v147 offset:22528
	ds_read_b128 v[222:225], v147 offset:23552
	global_load_lds_dwordx4 v[180:181], off
	s_add_i32 m0, s45, 0x2000
	s_add_u32 s60, s30, 0x40000
	v_lshl_add_u64 v[192:193], s[30:31], 0, v[130:131]
	s_addc_u32 s61, s31, 0
	s_add_i32 s45, s59, s50
	global_load_lds_dwordx4 v[192:193], off
	v_lshl_add_u64 v[202:203], s[60:61], 0, v[0:1]
	s_mov_b32 m0, s45
	v_lshl_add_u64 v[226:227], s[36:37], 0, v[132:133]
	global_load_lds_dwordx4 v[202:203], off
	v_lshl_add_u64 v[202:203], s[60:61], 0, v[130:131]
	s_add_i32 m0, s45, 0x2000
	s_nop 0
	global_load_lds_dwordx4 v[202:203], off
	v_lshl_add_u64 v[202:203], s[36:37], 0, v[134:135]
	s_mov_b32 m0, s51
	s_nop 0
	global_load_lds_dwordx4 v[202:203], off
	s_mov_b32 m0, s52
	s_nop 0
	global_load_lds_dwordx4 v[226:227], off
	s_waitcnt vmcnt(8)
	s_waitcnt lgkmcnt(0)
	s_barrier
	s_waitcnt lgkmcnt(0)
	v_mfma_f32_16x16x32_bf16 v[62:65], v[140:143], v[176:179], v[62:65]
	v_mfma_f32_16x16x32_bf16 v[58:61], v[152:155], v[176:179], v[58:61]
	v_mfma_f32_16x16x32_bf16 v[46:49], v[140:143], v[188:191], v[46:49]
	v_mfma_f32_16x16x32_bf16 v[42:45], v[152:155], v[188:191], v[42:45]
	v_mfma_f32_16x16x32_bf16 v[30:33], v[140:143], v[210:213], v[30:33]
	v_mfma_f32_16x16x32_bf16 v[26:29], v[152:155], v[210:213], v[26:29]
	v_mfma_f32_16x16x32_bf16 v[14:17], v[140:143], v[218:221], v[14:17]
	v_mfma_f32_16x16x32_bf16 v[10:13], v[152:155], v[218:221], v[10:13]
	v_mfma_f32_16x16x32_bf16 v[62:65], v[148:151], v[184:187], v[62:65]
	v_mfma_f32_16x16x32_bf16 v[58:61], v[156:159], v[184:187], v[58:61]
	v_mfma_f32_16x16x32_bf16 v[46:49], v[148:151], v[196:199], v[46:49]
	v_mfma_f32_16x16x32_bf16 v[42:45], v[156:159], v[196:199], v[42:45]
	v_mfma_f32_16x16x32_bf16 v[30:33], v[148:151], v[214:217], v[30:33]
	v_mfma_f32_16x16x32_bf16 v[26:29], v[156:159], v[214:217], v[26:29]
	v_mfma_f32_16x16x32_bf16 v[14:17], v[148:151], v[222:225], v[14:17]
	v_mfma_f32_16x16x32_bf16 v[10:13], v[156:159], v[222:225], v[10:13]
	v_mfma_f32_16x16x32_bf16 v[54:57], v[160:163], v[176:179], v[54:57]
	v_mfma_f32_16x16x32_bf16 v[50:53], v[168:171], v[176:179], v[50:53]
	v_mfma_f32_16x16x32_bf16 v[38:41], v[160:163], v[188:191], v[38:41]
	v_mfma_f32_16x16x32_bf16 v[34:37], v[168:171], v[188:191], v[34:37]
	v_mfma_f32_16x16x32_bf16 v[22:25], v[160:163], v[210:213], v[22:25]
	v_mfma_f32_16x16x32_bf16 v[18:21], v[168:171], v[210:213], v[18:21]
	v_mfma_f32_16x16x32_bf16 v[6:9], v[160:163], v[218:221], v[6:9]
	v_mfma_f32_16x16x32_bf16 v[2:5], v[168:171], v[218:221], v[2:5]
	v_mfma_f32_16x16x32_bf16 v[54:57], v[164:167], v[184:187], v[54:57]
	v_mfma_f32_16x16x32_bf16 v[50:53], v[172:175], v[184:187], v[50:53]
	v_mfma_f32_16x16x32_bf16 v[38:41], v[164:167], v[196:199], v[38:41]
	v_mfma_f32_16x16x32_bf16 v[34:37], v[172:175], v[196:199], v[34:37]
	v_mfma_f32_16x16x32_bf16 v[22:25], v[164:167], v[214:217], v[22:25]
	v_mfma_f32_16x16x32_bf16 v[18:21], v[172:175], v[214:217], v[18:21]
	v_mfma_f32_16x16x32_bf16 v[6:9], v[164:167], v[222:225], v[6:9]
	v_mfma_f32_16x16x32_bf16 v[2:5], v[172:175], v[222:225], v[2:5]
	s_barrier
	s_add_i32 s45, 0, 0x18000
	s_add_i32 s59, 0, 0x1c000
	v_add_u32_e32 v156, s45, v145
	v_add_u32_e32 v172, s59, v145
	ds_read_b128 v[140:143], v156
	ds_read_b128 v[148:151], v156 offset:1024
	ds_read_b128 v[152:155], v156 offset:2048
	ds_read_b128 v[156:159], v156 offset:3072
	ds_read_b128 v[160:163], v172
	ds_read_b128 v[164:167], v172 offset:1024
	ds_read_b128 v[168:171], v172 offset:2048
	ds_read_b128 v[172:175], v172 offset:3072
	s_add_u32 s36, s36, 0x40000
	s_addc_u32 s37, s37, 0
	s_mov_b32 m0, s53
	v_lshl_add_u64 v[228:229], s[36:37], 0, v[134:135]
	ds_read_b128 v[176:179], v147 offset:32768
	ds_read_b128 v[184:187], v147 offset:33792
	ds_read_b128 v[188:191], v147 offset:34816
	ds_read_b128 v[196:199], v147 offset:35840
	ds_read_b128 v[210:213], v147 offset:36864
	ds_read_b128 v[214:217], v147 offset:37888
	ds_read_b128 v[218:221], v147 offset:38912
	ds_read_b128 v[222:225], v147 offset:39936
	global_load_lds_dwordx4 v[228:229], off
	v_lshl_add_u64 v[228:229], s[36:37], 0, v[132:133]
	s_mov_b32 m0, s54
	s_nop 0
	global_load_lds_dwordx4 v[228:229], off
	s_waitcnt vmcnt(8)
	s_waitcnt lgkmcnt(0)
	s_barrier
	s_waitcnt lgkmcnt(0)
	v_mfma_f32_16x16x32_bf16 v[126:129], v[140:143], v[176:179], v[126:129]
	v_mfma_f32_16x16x32_bf16 v[122:125], v[152:155], v[176:179], v[122:125]
	v_mfma_f32_16x16x32_bf16 v[110:113], v[140:143], v[188:191], v[110:113]
	v_mfma_f32_16x16x32_bf16 v[106:109], v[152:155], v[188:191], v[106:109]
	v_mfma_f32_16x16x32_bf16 v[94:97], v[140:143], v[210:213], v[94:97]
	v_mfma_f32_16x16x32_bf16 v[90:93], v[152:155], v[210:213], v[90:93]
	v_mfma_f32_16x16x32_bf16 v[78:81], v[140:143], v[218:221], v[78:81]
	v_mfma_f32_16x16x32_bf16 v[74:77], v[152:155], v[218:221], v[74:77]
	v_mfma_f32_16x16x32_bf16 v[126:129], v[148:151], v[184:187], v[126:129]
	v_mfma_f32_16x16x32_bf16 v[122:125], v[156:159], v[184:187], v[122:125]
	v_mfma_f32_16x16x32_bf16 v[110:113], v[148:151], v[196:199], v[110:113]
	v_mfma_f32_16x16x32_bf16 v[106:109], v[156:159], v[196:199], v[106:109]
	v_mfma_f32_16x16x32_bf16 v[94:97], v[148:151], v[214:217], v[94:97]
	v_mfma_f32_16x16x32_bf16 v[90:93], v[156:159], v[214:217], v[90:93]
	v_mfma_f32_16x16x32_bf16 v[78:81], v[148:151], v[222:225], v[78:81]
	v_mfma_f32_16x16x32_bf16 v[74:77], v[156:159], v[222:225], v[74:77]
	v_mfma_f32_16x16x32_bf16 v[118:121], v[160:163], v[176:179], v[118:121]
	v_mfma_f32_16x16x32_bf16 v[114:117], v[168:171], v[176:179], v[114:117]
	v_mfma_f32_16x16x32_bf16 v[102:105], v[160:163], v[188:191], v[102:105]
	v_mfma_f32_16x16x32_bf16 v[98:101], v[168:171], v[188:191], v[98:101]
	v_mfma_f32_16x16x32_bf16 v[86:89], v[160:163], v[210:213], v[86:89]
	v_mfma_f32_16x16x32_bf16 v[82:85], v[168:171], v[210:213], v[82:85]
	v_mfma_f32_16x16x32_bf16 v[70:73], v[160:163], v[218:221], v[70:73]
	v_mfma_f32_16x16x32_bf16 v[66:69], v[168:171], v[218:221], v[66:69]
	v_mfma_f32_16x16x32_bf16 v[118:121], v[164:167], v[184:187], v[118:121]
	v_mfma_f32_16x16x32_bf16 v[114:117], v[172:175], v[184:187], v[114:117]
	v_mfma_f32_16x16x32_bf16 v[102:105], v[164:167], v[196:199], v[102:105]
	v_mfma_f32_16x16x32_bf16 v[98:101], v[172:175], v[196:199], v[98:101]
	v_mfma_f32_16x16x32_bf16 v[86:89], v[164:167], v[214:217], v[86:89]
	v_mfma_f32_16x16x32_bf16 v[82:85], v[172:175], v[214:217], v[82:85]
	v_mfma_f32_16x16x32_bf16 v[70:73], v[164:167], v[222:225], v[70:73]
	v_mfma_f32_16x16x32_bf16 v[66:69], v[172:175], v[222:225], v[66:69]
	s_barrier
	s_add_i32 s36, s45, s50
	v_lshl_add_u64 v[180:181], v[180:181], 0, s[22:23]
	s_mov_b32 m0, s36
	ds_read_b128 v[176:179], v147 offset:49152
	ds_read_b128 v[184:187], v147 offset:50176
	ds_read_b128 v[188:191], v147 offset:51200
	ds_read_b128 v[196:199], v147 offset:52224
	ds_read_b128 v[210:213], v147 offset:53248
	ds_read_b128 v[214:217], v147 offset:54272
	ds_read_b128 v[218:221], v147 offset:55296
	ds_read_b128 v[222:225], v147 offset:56320
	global_load_lds_dwordx4 v[180:181], off
	s_add_i32 m0, s36, 0x2000
	s_add_u32 s30, s30, 0x40080
	v_lshl_add_u64 v[180:181], v[192:193], 0, s[22:23]
	s_addc_u32 s31, s31, 0
	s_add_i32 s36, s59, s50
	global_load_lds_dwordx4 v[180:181], off
	v_lshl_add_u64 v[180:181], s[30:31], 0, v[0:1]
	s_mov_b32 m0, s36
	s_nop 0
	global_load_lds_dwordx4 v[180:181], off
	v_lshl_add_u64 v[180:181], s[30:31], 0, v[130:131]
	s_add_i32 m0, s36, 0x2000
	s_nop 0
	global_load_lds_dwordx4 v[180:181], off
	v_lshl_add_u64 v[180:181], v[202:203], 0, s[22:23]
	s_mov_b32 m0, s56
	s_nop 0
	global_load_lds_dwordx4 v[180:181], off
	v_lshl_add_u64 v[180:181], v[226:227], 0, s[22:23]
	s_mov_b32 m0, s57
	s_nop 0
	global_load_lds_dwordx4 v[180:181], off
	s_waitcnt vmcnt(8)
	s_waitcnt lgkmcnt(0)
	s_barrier
	s_waitcnt lgkmcnt(0)
	v_mfma_f32_16x16x32_bf16 v[62:65], v[140:143], v[176:179], v[62:65]
	v_mfma_f32_16x16x32_bf16 v[58:61], v[152:155], v[176:179], v[58:61]
	v_mfma_f32_16x16x32_bf16 v[46:49], v[140:143], v[188:191], v[46:49]
	v_mfma_f32_16x16x32_bf16 v[42:45], v[152:155], v[188:191], v[42:45]
	v_mfma_f32_16x16x32_bf16 v[30:33], v[140:143], v[210:213], v[30:33]
	v_mfma_f32_16x16x32_bf16 v[26:29], v[152:155], v[210:213], v[26:29]
	v_mfma_f32_16x16x32_bf16 v[14:17], v[140:143], v[218:221], v[14:17]
	v_mfma_f32_16x16x32_bf16 v[10:13], v[152:155], v[218:221], v[10:13]
	v_mfma_f32_16x16x32_bf16 v[62:65], v[148:151], v[184:187], v[62:65]
	v_mfma_f32_16x16x32_bf16 v[58:61], v[156:159], v[184:187], v[58:61]
	v_mfma_f32_16x16x32_bf16 v[46:49], v[148:151], v[196:199], v[46:49]
	v_mfma_f32_16x16x32_bf16 v[42:45], v[156:159], v[196:199], v[42:45]
	v_mfma_f32_16x16x32_bf16 v[30:33], v[148:151], v[214:217], v[30:33]
	v_mfma_f32_16x16x32_bf16 v[26:29], v[156:159], v[214:217], v[26:29]
	v_mfma_f32_16x16x32_bf16 v[14:17], v[148:151], v[222:225], v[14:17]
	v_mfma_f32_16x16x32_bf16 v[10:13], v[156:159], v[222:225], v[10:13]
	v_mfma_f32_16x16x32_bf16 v[54:57], v[160:163], v[176:179], v[54:57]
	v_mfma_f32_16x16x32_bf16 v[50:53], v[168:171], v[176:179], v[50:53]
	v_mfma_f32_16x16x32_bf16 v[38:41], v[160:163], v[188:191], v[38:41]
	v_mfma_f32_16x16x32_bf16 v[34:37], v[168:171], v[188:191], v[34:37]
	v_mfma_f32_16x16x32_bf16 v[22:25], v[160:163], v[210:213], v[22:25]
	v_mfma_f32_16x16x32_bf16 v[18:21], v[168:171], v[210:213], v[18:21]
	v_mfma_f32_16x16x32_bf16 v[6:9], v[160:163], v[218:221], v[6:9]
	v_mfma_f32_16x16x32_bf16 v[2:5], v[168:171], v[218:221], v[2:5]
	v_mfma_f32_16x16x32_bf16 v[54:57], v[164:167], v[184:187], v[54:57]
	v_mfma_f32_16x16x32_bf16 v[50:53], v[172:175], v[184:187], v[50:53]
	v_mfma_f32_16x16x32_bf16 v[38:41], v[164:167], v[196:199], v[38:41]
	v_mfma_f32_16x16x32_bf16 v[34:37], v[172:175], v[196:199], v[34:37]
	v_mfma_f32_16x16x32_bf16 v[22:25], v[164:167], v[214:217], v[22:25]
	v_mfma_f32_16x16x32_bf16 v[18:21], v[172:175], v[214:217], v[18:21]
	v_mfma_f32_16x16x32_bf16 v[6:9], v[164:167], v[222:225], v[6:9]
	v_mfma_f32_16x16x32_bf16 v[2:5], v[172:175], v[222:225], v[2:5]
	s_barrier
	s_add_i32 s35, s35, 2
	s_add_u32 s12, s12, 0x100
	s_addc_u32 s13, s13, 0
	s_add_u32 s26, s26, 0x100
	s_addc_u32 s28, s28, 0
	s_cmp_gt_u32 s35, 13
	s_cbranch_scc0 .LBB0_695
	s_setprio 0
	s_and_b64 vcc, exec, s[20:21]
	s_cbranch_vccz .LBB0_698
	s_barrier

.LBB0_791:
	s_ashr_i32 s15, s14, 31
	s_lshl_b64 s[20:21], s[14:15], 19
	s_add_u32 s20, s2, s20
	s_addc_u32 s21, s3, s21
	s_and_b64 s[30:31], s[4:5], exec
	s_cselect_b32 s15, s21, s35
	s_cselect_b32 s46, s20, s34
	s_ashr_i32 s13, s12, 31
	s_lshl_b64 s[30:31], s[12:13], 19
	s_add_u32 s30, s16, s30
	s_addc_u32 s31, s17, s31
	s_and_b64 s[40:41], s[4:5], exec
	s_cselect_b32 s13, s31, s37
	s_cselect_b32 s47, s30, s36
	s_add_u32 s34, s34, 0x40080
	s_addc_u32 s35, s35, 0
	s_add_u32 s48, s36, 0x100
	s_addc_u32 s49, s37, 0
	s_mov_b32 s50, -2
	v_mov_b64_e32 v[2:3], 0
	v_mov_b64_e32 v[4:5], 0
	v_mov_b64_e32 v[6:7], 0
	v_mov_b64_e32 v[8:9], 0
	v_mov_b64_e32 v[10:11], 0
	v_mov_b64_e32 v[12:13], 0
	v_mov_b64_e32 v[14:15], 0
	v_mov_b64_e32 v[16:17], 0
	v_mov_b64_e32 v[18:19], 0
	v_mov_b64_e32 v[20:21], 0
	v_mov_b64_e32 v[22:23], 0
	v_mov_b64_e32 v[24:25], 0
	v_mov_b64_e32 v[26:27], 0
	v_mov_b64_e32 v[28:29], 0
	v_mov_b64_e32 v[30:31], 0
	v_mov_b64_e32 v[32:33], 0
	v_mov_b64_e32 v[34:35], 0
	v_mov_b64_e32 v[36:37], 0
	v_mov_b64_e32 v[38:39], 0
	v_mov_b64_e32 v[40:41], 0
	v_mov_b64_e32 v[42:43], 0
	v_mov_b64_e32 v[44:45], 0
	v_mov_b64_e32 v[46:47], 0
	v_mov_b64_e32 v[48:49], 0
	v_mov_b64_e32 v[50:51], 0
	v_mov_b64_e32 v[52:53], 0
	v_mov_b64_e32 v[54:55], 0
	v_mov_b64_e32 v[56:57], 0
	v_mov_b64_e32 v[58:59], 0
	v_mov_b64_e32 v[60:61], 0
	v_mov_b64_e32 v[62:63], 0
	v_mov_b64_e32 v[64:65], 0
	v_mov_b64_e32 v[66:67], 0
	v_mov_b64_e32 v[68:69], 0
	v_mov_b64_e32 v[70:71], 0
	v_mov_b64_e32 v[72:73], 0
	v_mov_b64_e32 v[74:75], 0
	v_mov_b64_e32 v[76:77], 0
	v_mov_b64_e32 v[78:79], 0
	v_mov_b64_e32 v[80:81], 0
	v_mov_b64_e32 v[82:83], 0
	v_mov_b64_e32 v[84:85], 0
	v_mov_b64_e32 v[86:87], 0
	v_mov_b64_e32 v[88:89], 0
	v_mov_b64_e32 v[90:91], 0
	v_mov_b64_e32 v[92:93], 0
	v_mov_b64_e32 v[94:95], 0
	v_mov_b64_e32 v[96:97], 0
	v_mov_b64_e32 v[98:99], 0
	v_mov_b64_e32 v[100:101], 0
	v_mov_b64_e32 v[102:103], 0
	v_mov_b64_e32 v[104:105], 0
	v_mov_b64_e32 v[106:107], 0
	v_mov_b64_e32 v[108:109], 0
	v_mov_b64_e32 v[110:111], 0
	v_mov_b64_e32 v[112:113], 0
	v_mov_b64_e32 v[114:115], 0
	v_mov_b64_e32 v[116:117], 0
	v_mov_b64_e32 v[118:119], 0
	v_mov_b64_e32 v[120:121], 0
	v_mov_b64_e32 v[122:123], 0
	v_mov_b64_e32 v[124:125], 0
	v_mov_b64_e32 v[126:127], 0
	v_mov_b64_e32 v[128:129], 0
	s_cmp_lt_u32 s32, 0x100
	s_cbranch_scc1 .Lsprio_2
	s_setprio 1
.Lsprio_2:
.LBB0_792:
	s_add_u32 s36, s34, 0xfffc0080
	s_addc_u32 s37, s35, -1
	s_add_i32 s51, 0, 0x10000
	s_cmp_eq_u32 s50, 12
	s_cselect_b32 s41, s15, s37
	s_cselect_b32 s40, s46, s36
	v_add_u32_e32 v149, s51, v145
	s_cselect_b32 s37, s13, s49
	s_cselect_b32 s36, s47, s48
	s_add_i32 s54, 0, 0x14000
	ds_read_b128 v[140:143], v149
	ds_read_b128 v[150:153], v149 offset:1024
	ds_read_b128 v[154:157], v149 offset:2048
	ds_read_b128 v[158:161], v149 offset:3072
	v_add_u32_e32 v149, s54, v145
	ds_read_b128 v[162:165], v149
	ds_read_b128 v[166:169], v149 offset:1024
	ds_read_b128 v[170:173], v149 offset:2048
	ds_read_b128 v[174:177], v149 offset:3072
	v_lshl_add_u64 v[192:193], s[34:35], 0, v[136:137]
	s_add_i32 m0, s18, 0xc000
	ds_read_b128 v[178:181], v148
	ds_read_b128 v[184:187], v148 offset:1024
	ds_read_b128 v[188:191], v148 offset:2048
	ds_read_b128 v[196:199], v148 offset:3072
	ds_read_b128 v[210:213], v148 offset:4096
	ds_read_b128 v[214:217], v148 offset:5120
	ds_read_b128 v[218:221], v148 offset:6144
	ds_read_b128 v[222:225], v148 offset:7168
	global_load_lds_dwordx4 v[192:193], off
	v_lshl_add_u64 v[192:193], s[34:35], 0, v[138:139]
	s_add_i32 m0, s18, 0xe000
	s_nop 0
	global_load_lds_dwordx4 v[192:193], off
	s_waitcnt vmcnt(8)
	s_waitcnt lgkmcnt(0)
	s_barrier
	s_waitcnt lgkmcnt(0)
	v_mfma_f32_16x16x32_bf16 v[126:129], v[140:143], v[178:181], v[126:129]
	v_mfma_f32_16x16x32_bf16 v[122:125], v[154:157], v[178:181], v[122:125]
	v_mfma_f32_16x16x32_bf16 v[110:113], v[140:143], v[188:191], v[110:113]
	v_mfma_f32_16x16x32_bf16 v[106:109], v[154:157], v[188:191], v[106:109]
	v_mfma_f32_16x16x32_bf16 v[94:97], v[140:143], v[210:213], v[94:97]
	v_mfma_f32_16x16x32_bf16 v[90:93], v[154:157], v[210:213], v[90:93]
	v_mfma_f32_16x16x32_bf16 v[78:81], v[140:143], v[218:221], v[78:81]
	v_mfma_f32_16x16x32_bf16 v[74:77], v[154:157], v[218:221], v[74:77]
	v_mfma_f32_16x16x32_bf16 v[126:129], v[150:153], v[184:187], v[126:129]
	v_mfma_f32_16x16x32_bf16 v[122:125], v[158:161], v[184:187], v[122:125]
	v_mfma_f32_16x16x32_bf16 v[110:113], v[150:153], v[196:199], v[110:113]
	v_mfma_f32_16x16x32_bf16 v[106:109], v[158:161], v[196:199], v[106:109]
	v_mfma_f32_16x16x32_bf16 v[94:97], v[150:153], v[214:217], v[94:97]
	v_mfma_f32_16x16x32_bf16 v[90:93], v[158:161], v[214:217], v[90:93]
	v_mfma_f32_16x16x32_bf16 v[78:81], v[150:153], v[222:225], v[78:81]
	v_mfma_f32_16x16x32_bf16 v[74:77], v[158:161], v[222:225], v[74:77]
	v_mfma_f32_16x16x32_bf16 v[118:121], v[162:165], v[178:181], v[118:121]
	v_mfma_f32_16x16x32_bf16 v[114:117], v[170:173], v[178:181], v[114:117]
	v_mfma_f32_16x16x32_bf16 v[102:105], v[162:165], v[188:191], v[102:105]
	v_mfma_f32_16x16x32_bf16 v[98:101], v[170:173], v[188:191], v[98:101]
	v_mfma_f32_16x16x32_bf16 v[86:89], v[162:165], v[210:213], v[86:89]
	v_mfma_f32_16x16x32_bf16 v[82:85], v[170:173], v[210:213], v[82:85]
	v_mfma_f32_16x16x32_bf16 v[70:73], v[162:165], v[218:221], v[70:73]
	v_mfma_f32_16x16x32_bf16 v[66:69], v[170:173], v[218:221], v[66:69]
	v_mfma_f32_16x16x32_bf16 v[118:121], v[166:169], v[184:187], v[118:121]
	v_mfma_f32_16x16x32_bf16 v[114:117], v[174:177], v[184:187], v[114:117]
	v_mfma_f32_16x16x32_bf16 v[102:105], v[166:169], v[196:199], v[102:105]
	v_mfma_f32_16x16x32_bf16 v[98:101], v[174:177], v[196:199], v[98:101]
	v_mfma_f32_16x16x32_bf16 v[86:89], v[166:169], v[214:217], v[86:89]
	v_mfma_f32_16x16x32_bf16 v[82:85], v[174:177], v[214:217], v[82:85]
	v_mfma_f32_16x16x32_bf16 v[70:73], v[166:169], v[222:225], v[70:73]
	v_mfma_f32_16x16x32_bf16 v[66:69], v[174:177], v[222:225], v[66:69]
	s_barrier
	s_add_i32 s51, s51, s0
	v_lshl_add_u64 v[192:193], s[36:37], 0, v[0:1]
	s_mov_b32 m0, s51
	ds_read_b128 v[178:181], v148 offset:16384
	ds_read_b128 v[184:187], v148 offset:17408
	ds_read_b128 v[188:191], v148 offset:18432
	ds_read_b128 v[196:199], v148 offset:19456
	ds_read_b128 v[210:213], v148 offset:20480
	ds_read_b128 v[214:217], v148 offset:21504
	ds_read_b128 v[218:221], v148 offset:22528
	ds_read_b128 v[222:225], v148 offset:23552
	global_load_lds_dwordx4 v[192:193], off
	s_add_i32 m0, s51, 0x2000
	s_add_u32 s52, s36, 0x40000
	v_lshl_add_u64 v[202:203], s[36:37], 0, v[130:131]
	s_addc_u32 s53, s37, 0
	s_add_i32 s51, s54, s0
	global_load_lds_dwordx4 v[202:203], off
	v_lshl_add_u64 v[226:227], s[52:53], 0, v[0:1]
	s_mov_b32 m0, s51
	v_lshl_add_u64 v[228:229], s[40:41], 0, v[132:133]
	global_load_lds_dwordx4 v[226:227], off
	v_lshl_add_u64 v[226:227], s[52:53], 0, v[130:131]
	s_add_i32 m0, s51, 0x2000
	s_nop 0
	global_load_lds_dwordx4 v[226:227], off
	v_lshl_add_u64 v[226:227], s[40:41], 0, v[134:135]
	s_mov_b32 m0, s18
	s_nop 0
	global_load_lds_dwordx4 v[226:227], off
	s_mov_b32 m0, s19
	s_nop 0
	global_load_lds_dwordx4 v[228:229], off
	s_waitcnt vmcnt(8)
	s_waitcnt lgkmcnt(0)
	s_barrier
	s_waitcnt lgkmcnt(0)
	v_mfma_f32_16x16x32_bf16 v[62:65], v[140:143], v[178:181], v[62:65]
	v_mfma_f32_16x16x32_bf16 v[58:61], v[154:157], v[178:181], v[58:61]
	v_mfma_f32_16x16x32_bf16 v[46:49], v[140:143], v[188:191], v[46:49]
	v_mfma_f32_16x16x32_bf16 v[42:45], v[154:157], v[188:191], v[42:45]
	v_mfma_f32_16x16x32_bf16 v[30:33], v[140:143], v[210:213], v[30:33]
	v_mfma_f32_16x16x32_bf16 v[26:29], v[154:157], v[210:213], v[26:29]
	v_mfma_f32_16x16x32_bf16 v[14:17], v[140:143], v[218:221], v[14:17]
	v_mfma_f32_16x16x32_bf16 v[10:13], v[154:157], v[218:221], v[10:13]
	v_mfma_f32_16x16x32_bf16 v[62:65], v[150:153], v[184:187], v[62:65]
	v_mfma_f32_16x16x32_bf16 v[58:61], v[158:161], v[184:187], v[58:61]
	v_mfma_f32_16x16x32_bf16 v[46:49], v[150:153], v[196:199], v[46:49]
	v_mfma_f32_16x16x32_bf16 v[42:45], v[158:161], v[196:199], v[42:45]
	v_mfma_f32_16x16x32_bf16 v[30:33], v[150:153], v[214:217], v[30:33]
	v_mfma_f32_16x16x32_bf16 v[26:29], v[158:161], v[214:217], v[26:29]
	v_mfma_f32_16x16x32_bf16 v[14:17], v[150:153], v[222:225], v[14:17]
	v_mfma_f32_16x16x32_bf16 v[10:13], v[158:161], v[222:225], v[10:13]
	v_mfma_f32_16x16x32_bf16 v[54:57], v[162:165], v[178:181], v[54:57]
	v_mfma_f32_16x16x32_bf16 v[50:53], v[170:173], v[178:181], v[50:53]
	v_mfma_f32_16x16x32_bf16 v[38:41], v[162:165], v[188:191], v[38:41]
	v_mfma_f32_16x16x32_bf16 v[34:37], v[170:173], v[188:191], v[34:37]
	v_mfma_f32_16x16x32_bf16 v[22:25], v[162:165], v[210:213], v[22:25]
	v_mfma_f32_16x16x32_bf16 v[18:21], v[170:173], v[210:213], v[18:21]
	v_mfma_f32_16x16x32_bf16 v[6:9], v[162:165], v[218:221], v[6:9]
	v_mfma_f32_16x16x32_bf16 v[2:5], v[170:173], v[218:221], v[2:5]
	v_mfma_f32_16x16x32_bf16 v[54:57], v[166:169], v[184:187], v[54:57]
	v_mfma_f32_16x16x32_bf16 v[50:53], v[174:177], v[184:187], v[50:53]
	v_mfma_f32_16x16x32_bf16 v[38:41], v[166:169], v[196:199], v[38:41]
	v_mfma_f32_16x16x32_bf16 v[34:37], v[174:177], v[196:199], v[34:37]
	v_mfma_f32_16x16x32_bf16 v[22:25], v[166:169], v[214:217], v[22:25]
	v_mfma_f32_16x16x32_bf16 v[18:21], v[174:177], v[214:217], v[18:21]
	v_mfma_f32_16x16x32_bf16 v[6:9], v[166:169], v[222:225], v[6:9]
	v_mfma_f32_16x16x32_bf16 v[2:5], v[174:177], v[222:225], v[2:5]
	s_barrier
	s_add_i32 s51, 0, 0x18000
	v_add_u32_e32 v149, s51, v145
	s_add_i32 s52, 0, 0x1c000
	ds_read_b128 v[140:143], v149
	ds_read_b128 v[150:153], v149 offset:1024
	ds_read_b128 v[154:157], v149 offset:2048
	ds_read_b128 v[158:161], v149 offset:3072
	v_add_u32_e32 v149, s52, v145
	ds_read_b128 v[162:165], v149
	ds_read_b128 v[166:169], v149 offset:1024
	ds_read_b128 v[170:173], v149 offset:2048
	ds_read_b128 v[174:177], v149 offset:3072
	s_add_u32 s40, s40, 0x40000
	s_addc_u32 s41, s41, 0
	s_mov_b32 m0, s24
	v_lshl_add_u64 v[230:231], s[40:41], 0, v[134:135]
	ds_read_b128 v[178:181], v148 offset:32768
	ds_read_b128 v[184:187], v148 offset:33792
	ds_read_b128 v[188:191], v148 offset:34816
	ds_read_b128 v[196:199], v148 offset:35840
	ds_read_b128 v[210:213], v148 offset:36864
	ds_read_b128 v[214:217], v148 offset:37888
	ds_read_b128 v[218:221], v148 offset:38912
	ds_read_b128 v[222:225], v148 offset:39936
	global_load_lds_dwordx4 v[230:231], off
	v_lshl_add_u64 v[230:231], s[40:41], 0, v[132:133]
	s_mov_b32 m0, s25
	s_nop 0
	global_load_lds_dwordx4 v[230:231], off
	s_waitcnt vmcnt(8)
	s_waitcnt lgkmcnt(0)
	s_barrier
	s_waitcnt lgkmcnt(0)
	v_mfma_f32_16x16x32_bf16 v[126:129], v[140:143], v[178:181], v[126:129]
	v_mfma_f32_16x16x32_bf16 v[122:125], v[154:157], v[178:181], v[122:125]
	v_mfma_f32_16x16x32_bf16 v[110:113], v[140:143], v[188:191], v[110:113]
	v_mfma_f32_16x16x32_bf16 v[106:109], v[154:157], v[188:191], v[106:109]
	v_mfma_f32_16x16x32_bf16 v[94:97], v[140:143], v[210:213], v[94:97]
	v_mfma_f32_16x16x32_bf16 v[90:93], v[154:157], v[210:213], v[90:93]
	v_mfma_f32_16x16x32_bf16 v[78:81], v[140:143], v[218:221], v[78:81]
	v_mfma_f32_16x16x32_bf16 v[74:77], v[154:157], v[218:221], v[74:77]
	v_mfma_f32_16x16x32_bf16 v[126:129], v[150:153], v[184:187], v[126:129]
	v_mfma_f32_16x16x32_bf16 v[122:125], v[158:161], v[184:187], v[122:125]
	v_mfma_f32_16x16x32_bf16 v[110:113], v[150:153], v[196:199], v[110:113]
	v_mfma_f32_16x16x32_bf16 v[106:109], v[158:161], v[196:199], v[106:109]
	v_mfma_f32_16x16x32_bf16 v[94:97], v[150:153], v[214:217], v[94:97]
	v_mfma_f32_16x16x32_bf16 v[90:93], v[158:161], v[214:217], v[90:93]
	v_mfma_f32_16x16x32_bf16 v[78:81], v[150:153], v[222:225], v[78:81]
	v_mfma_f32_16x16x32_bf16 v[74:77], v[158:161], v[222:225], v[74:77]
	v_mfma_f32_16x16x32_bf16 v[118:121], v[162:165], v[178:181], v[118:121]
	v_mfma_f32_16x16x32_bf16 v[114:117], v[170:173], v[178:181], v[114:117]
	v_mfma_f32_16x16x32_bf16 v[102:105], v[162:165], v[188:191], v[102:105]
	v_mfma_f32_16x16x32_bf16 v[98:101], v[170:173], v[188:191], v[98:101]
	v_mfma_f32_16x16x32_bf16 v[86:89], v[162:165], v[210:213], v[86:89]
	v_mfma_f32_16x16x32_bf16 v[82:85], v[170:173], v[210:213], v[82:85]
	v_mfma_f32_16x16x32_bf16 v[70:73], v[162:165], v[218:221], v[70:73]
	v_mfma_f32_16x16x32_bf16 v[66:69], v[170:173], v[218:221], v[66:69]
	v_mfma_f32_16x16x32_bf16 v[118:121], v[166:169], v[184:187], v[118:121]
	v_mfma_f32_16x16x32_bf16 v[114:117], v[174:177], v[184:187], v[114:117]
	v_mfma_f32_16x16x32_bf16 v[102:105], v[166:169], v[196:199], v[102:105]
	v_mfma_f32_16x16x32_bf16 v[98:101], v[174:177], v[196:199], v[98:101]
	v_mfma_f32_16x16x32_bf16 v[86:89], v[166:169], v[214:217], v[86:89]
	v_mfma_f32_16x16x32_bf16 v[82:85], v[174:177], v[214:217], v[82:85]
	v_mfma_f32_16x16x32_bf16 v[70:73], v[166:169], v[222:225], v[70:73]
	v_mfma_f32_16x16x32_bf16 v[66:69], v[174:177], v[222:225], v[66:69]
	s_barrier
	s_add_i32 s40, s51, s0
	v_lshl_add_u64 v[192:193], v[192:193], 0, s[22:23]
	s_mov_b32 m0, s40
	ds_read_b128 v[178:181], v148 offset:49152
	ds_read_b128 v[184:187], v148 offset:50176
	ds_read_b128 v[188:191], v148 offset:51200
	ds_read_b128 v[196:199], v148 offset:52224
	ds_read_b128 v[210:213], v148 offset:53248
	ds_read_b128 v[214:217], v148 offset:54272
	ds_read_b128 v[218:221], v148 offset:55296
	ds_read_b128 v[222:225], v148 offset:56320
	global_load_lds_dwordx4 v[192:193], off
	s_add_i32 m0, s40, 0x2000
	s_add_u32 s36, s36, 0x40080
	v_lshl_add_u64 v[192:193], v[202:203], 0, s[22:23]
	s_addc_u32 s37, s37, 0
	s_add_i32 s40, s52, s0
	global_load_lds_dwordx4 v[192:193], off
	v_lshl_add_u64 v[192:193], s[36:37], 0, v[0:1]
	s_mov_b32 m0, s40
	s_nop 0
	global_load_lds_dwordx4 v[192:193], off
	v_lshl_add_u64 v[192:193], s[36:37], 0, v[130:131]
	s_add_i32 m0, s40, 0x2000
	s_nop 0
	global_load_lds_dwordx4 v[192:193], off
	v_lshl_add_u64 v[192:193], v[226:227], 0, s[22:23]
	s_mov_b32 m0, s26
	s_nop 0
	global_load_lds_dwordx4 v[192:193], off
	v_lshl_add_u64 v[192:193], v[228:229], 0, s[22:23]
	s_mov_b32 m0, s28
	s_nop 0
	global_load_lds_dwordx4 v[192:193], off
	s_waitcnt vmcnt(8)
	s_waitcnt lgkmcnt(0)
	s_barrier
	s_waitcnt lgkmcnt(0)
	v_mfma_f32_16x16x32_bf16 v[62:65], v[140:143], v[178:181], v[62:65]
	v_mfma_f32_16x16x32_bf16 v[58:61], v[154:157], v[178:181], v[58:61]
	v_mfma_f32_16x16x32_bf16 v[46:49], v[140:143], v[188:191], v[46:49]
	v_mfma_f32_16x16x32_bf16 v[42:45], v[154:157], v[188:191], v[42:45]
	v_mfma_f32_16x16x32_bf16 v[30:33], v[140:143], v[210:213], v[30:33]
	v_mfma_f32_16x16x32_bf16 v[26:29], v[154:157], v[210:213], v[26:29]
	v_mfma_f32_16x16x32_bf16 v[14:17], v[140:143], v[218:221], v[14:17]
	v_mfma_f32_16x16x32_bf16 v[10:13], v[154:157], v[218:221], v[10:13]
	v_mfma_f32_16x16x32_bf16 v[62:65], v[150:153], v[184:187], v[62:65]
	v_mfma_f32_16x16x32_bf16 v[58:61], v[158:161], v[184:187], v[58:61]
	v_mfma_f32_16x16x32_bf16 v[46:49], v[150:153], v[196:199], v[46:49]
	v_mfma_f32_16x16x32_bf16 v[42:45], v[158:161], v[196:199], v[42:45]
	v_mfma_f32_16x16x32_bf16 v[30:33], v[150:153], v[214:217], v[30:33]
	v_mfma_f32_16x16x32_bf16 v[26:29], v[158:161], v[214:217], v[26:29]
	v_mfma_f32_16x16x32_bf16 v[14:17], v[150:153], v[222:225], v[14:17]
	v_mfma_f32_16x16x32_bf16 v[10:13], v[158:161], v[222:225], v[10:13]
	v_mfma_f32_16x16x32_bf16 v[54:57], v[162:165], v[178:181], v[54:57]
	v_mfma_f32_16x16x32_bf16 v[50:53], v[170:173], v[178:181], v[50:53]
	v_mfma_f32_16x16x32_bf16 v[38:41], v[162:165], v[188:191], v[38:41]
	v_mfma_f32_16x16x32_bf16 v[34:37], v[170:173], v[188:191], v[34:37]
	v_mfma_f32_16x16x32_bf16 v[22:25], v[162:165], v[210:213], v[22:25]
	v_mfma_f32_16x16x32_bf16 v[18:21], v[170:173], v[210:213], v[18:21]
	v_mfma_f32_16x16x32_bf16 v[6:9], v[162:165], v[218:221], v[6:9]
	v_mfma_f32_16x16x32_bf16 v[2:5], v[170:173], v[218:221], v[2:5]
	v_mfma_f32_16x16x32_bf16 v[54:57], v[166:169], v[184:187], v[54:57]
	v_mfma_f32_16x16x32_bf16 v[50:53], v[174:177], v[184:187], v[50:53]
	v_mfma_f32_16x16x32_bf16 v[38:41], v[166:169], v[196:199], v[38:41]
	v_mfma_f32_16x16x32_bf16 v[34:37], v[174:177], v[196:199], v[34:37]
	v_mfma_f32_16x16x32_bf16 v[22:25], v[166:169], v[214:217], v[22:25]
	v_mfma_f32_16x16x32_bf16 v[18:21], v[174:177], v[214:217], v[18:21]
	v_mfma_f32_16x16x32_bf16 v[6:9], v[166:169], v[222:225], v[6:9]
	v_mfma_f32_16x16x32_bf16 v[2:5], v[174:177], v[222:225], v[2:5]
	s_barrier
	s_add_i32 s50, s50, 2
	s_add_u32 s34, s34, 0x100
	s_addc_u32 s35, s35, 0
	s_add_u32 s48, s48, 0x100
	s_addc_u32 s49, s49, 0
	s_cmp_gt_u32 s50, 13
	s_cbranch_scc0 .LBB0_792
	s_setprio 0
	s_and_b64 vcc, exec, s[10:11]
	s_cbranch_vccz .LBB0_795
	s_barrier

.LBB0_863:
	s_ashr_i32 s45, s44, 31
	s_lshl_b64 s[24:25], s[44:45], 21
	s_add_u32 s46, s17, s24
	s_addc_u32 s47, s18, s25
	s_and_b64 s[24:25], s[42:43], exec
	s_cselect_b32 s3, s47, s13
	s_cselect_b32 s16, s46, s12
	s_ashr_i32 s35, s34, 31
	s_lshl_b64 s[24:25], s[34:35], 21
	s_add_u32 s48, s19, s24
	s_addc_u32 s49, s29, s25
	s_and_b64 s[24:25], s[42:43], exec
	s_cselect_b32 s24, s49, s31
	s_cselect_b32 s25, s48, s30
	s_add_u32 s12, s12, 0x100080
	s_addc_u32 s13, s13, 0
	s_add_u32 s26, s30, 0x100
	s_addc_u32 s28, s31, 0
	s_mov_b32 s35, -2
	v_mov_b64_e32 v[2:3], 0
	v_mov_b64_e32 v[4:5], 0
	v_mov_b64_e32 v[6:7], 0
	v_mov_b64_e32 v[8:9], 0
	v_mov_b64_e32 v[10:11], 0
	v_mov_b64_e32 v[12:13], 0
	v_mov_b64_e32 v[14:15], 0
	v_mov_b64_e32 v[16:17], 0
	v_mov_b64_e32 v[18:19], 0
	v_mov_b64_e32 v[20:21], 0
	v_mov_b64_e32 v[22:23], 0
	v_mov_b64_e32 v[24:25], 0
	v_mov_b64_e32 v[26:27], 0
	v_mov_b64_e32 v[28:29], 0
	v_mov_b64_e32 v[30:31], 0
	v_mov_b64_e32 v[32:33], 0
	v_mov_b64_e32 v[34:35], 0
	v_mov_b64_e32 v[36:37], 0
	v_mov_b64_e32 v[38:39], 0
	v_mov_b64_e32 v[40:41], 0
	v_mov_b64_e32 v[42:43], 0
	v_mov_b64_e32 v[44:45], 0
	v_mov_b64_e32 v[46:47], 0
	v_mov_b64_e32 v[48:49], 0
	v_mov_b64_e32 v[50:51], 0
	v_mov_b64_e32 v[52:53], 0
	v_mov_b64_e32 v[54:55], 0
	v_mov_b64_e32 v[56:57], 0
	v_mov_b64_e32 v[58:59], 0
	v_mov_b64_e32 v[60:61], 0
	v_mov_b64_e32 v[62:63], 0
	v_mov_b64_e32 v[64:65], 0
	v_mov_b64_e32 v[66:67], 0
	v_mov_b64_e32 v[68:69], 0
	v_mov_b64_e32 v[70:71], 0
	v_mov_b64_e32 v[72:73], 0
	v_mov_b64_e32 v[74:75], 0
	v_mov_b64_e32 v[76:77], 0
	v_mov_b64_e32 v[78:79], 0
	v_mov_b64_e32 v[80:81], 0
	v_mov_b64_e32 v[82:83], 0
	v_mov_b64_e32 v[84:85], 0
	v_mov_b64_e32 v[86:87], 0
	v_mov_b64_e32 v[88:89], 0
	v_mov_b64_e32 v[90:91], 0
	v_mov_b64_e32 v[92:93], 0
	v_mov_b64_e32 v[94:95], 0
	v_mov_b64_e32 v[96:97], 0
	v_mov_b64_e32 v[98:99], 0
	v_mov_b64_e32 v[100:101], 0
	v_mov_b64_e32 v[102:103], 0
	v_mov_b64_e32 v[104:105], 0
	v_mov_b64_e32 v[106:107], 0
	v_mov_b64_e32 v[108:109], 0
	v_mov_b64_e32 v[110:111], 0
	v_mov_b64_e32 v[112:113], 0
	v_mov_b64_e32 v[114:115], 0
	v_mov_b64_e32 v[116:117], 0
	v_mov_b64_e32 v[118:119], 0
	v_mov_b64_e32 v[120:121], 0
	v_mov_b64_e32 v[122:123], 0
	v_mov_b64_e32 v[124:125], 0
	v_mov_b64_e32 v[126:127], 0
	v_mov_b64_e32 v[128:129], 0
	s_cmp_lt_u32 s32, 0x100
	s_cbranch_scc1 .Lsprio_3
	s_setprio 1
.Lsprio_3:
.LBB0_864:
	s_add_u32 s30, s12, 0xfff00080
	s_addc_u32 s31, s13, -1
	s_add_i32 s45, 0, 0x10000
	s_cmp_eq_u32 s35, 60
	s_cselect_b32 s37, s3, s31
	s_cselect_b32 s36, s16, s30
	s_cselect_b32 s31, s24, s28
	s_cselect_b32 s30, s25, s26
	s_add_i32 s59, 0, 0x14000
	v_add_u32_e32 v156, s45, v145
	v_add_u32_e32 v172, s59, v145
	ds_read_b128 v[140:143], v156
	ds_read_b128 v[148:151], v156 offset:1024
	ds_read_b128 v[152:155], v156 offset:2048
	ds_read_b128 v[156:159], v156 offset:3072
	ds_read_b128 v[160:163], v172
	ds_read_b128 v[164:167], v172 offset:1024
	ds_read_b128 v[168:171], v172 offset:2048
	ds_read_b128 v[172:175], v172 offset:3072
	v_lshl_add_u64 v[180:181], s[12:13], 0, v[136:137]
	s_add_i32 m0, s51, 0xc000
	ds_read_b128 v[176:179], v147
	ds_read_b128 v[184:187], v147 offset:1024
	ds_read_b128 v[188:191], v147 offset:2048
	ds_read_b128 v[196:199], v147 offset:3072
	ds_read_b128 v[210:213], v147 offset:4096
	ds_read_b128 v[214:217], v147 offset:5120
	ds_read_b128 v[218:221], v147 offset:6144
	ds_read_b128 v[222:225], v147 offset:7168
	global_load_lds_dwordx4 v[180:181], off
	v_lshl_add_u64 v[180:181], s[12:13], 0, v[138:139]
	s_add_i32 m0, s51, 0xe000
	s_nop 0
	global_load_lds_dwordx4 v[180:181], off
	s_waitcnt vmcnt(8)
	s_waitcnt lgkmcnt(0)
	s_barrier
	s_waitcnt lgkmcnt(0)
	v_mfma_f32_16x16x32_bf16 v[126:129], v[140:143], v[176:179], v[126:129]
	v_mfma_f32_16x16x32_bf16 v[122:125], v[152:155], v[176:179], v[122:125]
	v_mfma_f32_16x16x32_bf16 v[110:113], v[140:143], v[188:191], v[110:113]
	v_mfma_f32_16x16x32_bf16 v[106:109], v[152:155], v[188:191], v[106:109]
	v_mfma_f32_16x16x32_bf16 v[94:97], v[140:143], v[210:213], v[94:97]
	v_mfma_f32_16x16x32_bf16 v[90:93], v[152:155], v[210:213], v[90:93]
	v_mfma_f32_16x16x32_bf16 v[78:81], v[140:143], v[218:221], v[78:81]
	v_mfma_f32_16x16x32_bf16 v[74:77], v[152:155], v[218:221], v[74:77]
	v_mfma_f32_16x16x32_bf16 v[126:129], v[148:151], v[184:187], v[126:129]
	v_mfma_f32_16x16x32_bf16 v[122:125], v[156:159], v[184:187], v[122:125]
	v_mfma_f32_16x16x32_bf16 v[110:113], v[148:151], v[196:199], v[110:113]
	v_mfma_f32_16x16x32_bf16 v[106:109], v[156:159], v[196:199], v[106:109]
	v_mfma_f32_16x16x32_bf16 v[94:97], v[148:151], v[214:217], v[94:97]
	v_mfma_f32_16x16x32_bf16 v[90:93], v[156:159], v[214:217], v[90:93]
	v_mfma_f32_16x16x32_bf16 v[78:81], v[148:151], v[222:225], v[78:81]
	v_mfma_f32_16x16x32_bf16 v[74:77], v[156:159], v[222:225], v[74:77]
	v_mfma_f32_16x16x32_bf16 v[118:121], v[160:163], v[176:179], v[118:121]
	v_mfma_f32_16x16x32_bf16 v[114:117], v[168:171], v[176:179], v[114:117]
	v_mfma_f32_16x16x32_bf16 v[102:105], v[160:163], v[188:191], v[102:105]
	v_mfma_f32_16x16x32_bf16 v[98:101], v[168:171], v[188:191], v[98:101]
	v_mfma_f32_16x16x32_bf16 v[86:89], v[160:163], v[210:213], v[86:89]
	v_mfma_f32_16x16x32_bf16 v[82:85], v[168:171], v[210:213], v[82:85]
	v_mfma_f32_16x16x32_bf16 v[70:73], v[160:163], v[218:221], v[70:73]
	v_mfma_f32_16x16x32_bf16 v[66:69], v[168:171], v[218:221], v[66:69]
	v_mfma_f32_16x16x32_bf16 v[118:121], v[164:167], v[184:187], v[118:121]
	v_mfma_f32_16x16x32_bf16 v[114:117], v[172:175], v[184:187], v[114:117]
	v_mfma_f32_16x16x32_bf16 v[102:105], v[164:167], v[196:199], v[102:105]
	v_mfma_f32_16x16x32_bf16 v[98:101], v[172:175], v[196:199], v[98:101]
	v_mfma_f32_16x16x32_bf16 v[86:89], v[164:167], v[214:217], v[86:89]
	v_mfma_f32_16x16x32_bf16 v[82:85], v[172:175], v[214:217], v[82:85]
	v_mfma_f32_16x16x32_bf16 v[70:73], v[164:167], v[222:225], v[70:73]
	v_mfma_f32_16x16x32_bf16 v[66:69], v[172:175], v[222:225], v[66:69]
	s_barrier
	s_add_i32 s45, s45, s50
	v_lshl_add_u64 v[180:181], s[30:31], 0, v[0:1]
	s_mov_b32 m0, s45
	ds_read_b128 v[176:179], v147 offset:16384
	ds_read_b128 v[184:187], v147 offset:17408
	ds_read_b128 v[188:191], v147 offset:18432
	ds_read_b128 v[196:199], v147 offset:19456
	ds_read_b128 v[210:213], v147 offset:20480
	ds_read_b128 v[214:217], v147 offset:21504
	ds_read_b128 v[218:221], v147 offset:22528
	ds_read_b128 v[222:225], v147 offset:23552
	global_load_lds_dwordx4 v[180:181], off
	s_add_i32 m0, s45, 0x2000
	s_add_u32 s60, s30, 0x100000
	v_lshl_add_u64 v[192:193], s[30:31], 0, v[130:131]
	s_addc_u32 s61, s31, 0
	s_add_i32 s45, s59, s50
	global_load_lds_dwordx4 v[192:193], off
	v_lshl_add_u64 v[202:203], s[60:61], 0, v[0:1]
	s_mov_b32 m0, s45
	v_lshl_add_u64 v[226:227], s[36:37], 0, v[132:133]
	global_load_lds_dwordx4 v[202:203], off
	v_lshl_add_u64 v[202:203], s[60:61], 0, v[130:131]
	s_add_i32 m0, s45, 0x2000
	s_nop 0
	global_load_lds_dwordx4 v[202:203], off
	v_lshl_add_u64 v[202:203], s[36:37], 0, v[134:135]
	s_mov_b32 m0, s51
	s_nop 0
	global_load_lds_dwordx4 v[202:203], off
	s_mov_b32 m0, s52
	s_nop 0
	global_load_lds_dwordx4 v[226:227], off
	s_waitcnt vmcnt(8)
	s_waitcnt lgkmcnt(0)
	s_barrier
	s_waitcnt lgkmcnt(0)
	v_mfma_f32_16x16x32_bf16 v[62:65], v[140:143], v[176:179], v[62:65]
	v_mfma_f32_16x16x32_bf16 v[58:61], v[152:155], v[176:179], v[58:61]
	v_mfma_f32_16x16x32_bf16 v[46:49], v[140:143], v[188:191], v[46:49]
	v_mfma_f32_16x16x32_bf16 v[42:45], v[152:155], v[188:191], v[42:45]
	v_mfma_f32_16x16x32_bf16 v[30:33], v[140:143], v[210:213], v[30:33]
	v_mfma_f32_16x16x32_bf16 v[26:29], v[152:155], v[210:213], v[26:29]
	v_mfma_f32_16x16x32_bf16 v[14:17], v[140:143], v[218:221], v[14:17]
	v_mfma_f32_16x16x32_bf16 v[10:13], v[152:155], v[218:221], v[10:13]
	v_mfma_f32_16x16x32_bf16 v[62:65], v[148:151], v[184:187], v[62:65]
	v_mfma_f32_16x16x32_bf16 v[58:61], v[156:159], v[184:187], v[58:61]
	v_mfma_f32_16x16x32_bf16 v[46:49], v[148:151], v[196:199], v[46:49]
	v_mfma_f32_16x16x32_bf16 v[42:45], v[156:159], v[196:199], v[42:45]
	v_mfma_f32_16x16x32_bf16 v[30:33], v[148:151], v[214:217], v[30:33]
	v_mfma_f32_16x16x32_bf16 v[26:29], v[156:159], v[214:217], v[26:29]
	v_mfma_f32_16x16x32_bf16 v[14:17], v[148:151], v[222:225], v[14:17]
	v_mfma_f32_16x16x32_bf16 v[10:13], v[156:159], v[222:225], v[10:13]
	v_mfma_f32_16x16x32_bf16 v[54:57], v[160:163], v[176:179], v[54:57]
	v_mfma_f32_16x16x32_bf16 v[50:53], v[168:171], v[176:179], v[50:53]
	v_mfma_f32_16x16x32_bf16 v[38:41], v[160:163], v[188:191], v[38:41]
	v_mfma_f32_16x16x32_bf16 v[34:37], v[168:171], v[188:191], v[34:37]
	v_mfma_f32_16x16x32_bf16 v[22:25], v[160:163], v[210:213], v[22:25]
	v_mfma_f32_16x16x32_bf16 v[18:21], v[168:171], v[210:213], v[18:21]
	v_mfma_f32_16x16x32_bf16 v[6:9], v[160:163], v[218:221], v[6:9]
	v_mfma_f32_16x16x32_bf16 v[2:5], v[168:171], v[218:221], v[2:5]
	v_mfma_f32_16x16x32_bf16 v[54:57], v[164:167], v[184:187], v[54:57]
	v_mfma_f32_16x16x32_bf16 v[50:53], v[172:175], v[184:187], v[50:53]
	v_mfma_f32_16x16x32_bf16 v[38:41], v[164:167], v[196:199], v[38:41]
	v_mfma_f32_16x16x32_bf16 v[34:37], v[172:175], v[196:199], v[34:37]
	v_mfma_f32_16x16x32_bf16 v[22:25], v[164:167], v[214:217], v[22:25]
	v_mfma_f32_16x16x32_bf16 v[18:21], v[172:175], v[214:217], v[18:21]
	v_mfma_f32_16x16x32_bf16 v[6:9], v[164:167], v[222:225], v[6:9]
	v_mfma_f32_16x16x32_bf16 v[2:5], v[172:175], v[222:225], v[2:5]
	s_barrier
	s_add_i32 s45, 0, 0x18000
	s_add_i32 s59, 0, 0x1c000
	v_add_u32_e32 v156, s45, v145
	v_add_u32_e32 v172, s59, v145
	ds_read_b128 v[140:143], v156
	ds_read_b128 v[148:151], v156 offset:1024
	ds_read_b128 v[152:155], v156 offset:2048
	ds_read_b128 v[156:159], v156 offset:3072
	ds_read_b128 v[160:163], v172
	ds_read_b128 v[164:167], v172 offset:1024
	ds_read_b128 v[168:171], v172 offset:2048
	ds_read_b128 v[172:175], v172 offset:3072
	s_add_u32 s36, s36, 0x100000
	s_addc_u32 s37, s37, 0
	s_mov_b32 m0, s53
	v_lshl_add_u64 v[228:229], s[36:37], 0, v[134:135]
	ds_read_b128 v[176:179], v147 offset:32768
	ds_read_b128 v[184:187], v147 offset:33792
	ds_read_b128 v[188:191], v147 offset:34816
	ds_read_b128 v[196:199], v147 offset:35840
	ds_read_b128 v[210:213], v147 offset:36864
	ds_read_b128 v[214:217], v147 offset:37888
	ds_read_b128 v[218:221], v147 offset:38912
	ds_read_b128 v[222:225], v147 offset:39936
	global_load_lds_dwordx4 v[228:229], off
	v_lshl_add_u64 v[228:229], s[36:37], 0, v[132:133]
	s_mov_b32 m0, s54
	s_nop 0
	global_load_lds_dwordx4 v[228:229], off
	s_waitcnt vmcnt(8)
	s_waitcnt lgkmcnt(0)
	s_barrier
	s_waitcnt lgkmcnt(0)
	v_mfma_f32_16x16x32_bf16 v[126:129], v[140:143], v[176:179], v[126:129]
	v_mfma_f32_16x16x32_bf16 v[122:125], v[152:155], v[176:179], v[122:125]
	v_mfma_f32_16x16x32_bf16 v[110:113], v[140:143], v[188:191], v[110:113]
	v_mfma_f32_16x16x32_bf16 v[106:109], v[152:155], v[188:191], v[106:109]
	v_mfma_f32_16x16x32_bf16 v[94:97], v[140:143], v[210:213], v[94:97]
	v_mfma_f32_16x16x32_bf16 v[90:93], v[152:155], v[210:213], v[90:93]
	v_mfma_f32_16x16x32_bf16 v[78:81], v[140:143], v[218:221], v[78:81]
	v_mfma_f32_16x16x32_bf16 v[74:77], v[152:155], v[218:221], v[74:77]
	v_mfma_f32_16x16x32_bf16 v[126:129], v[148:151], v[184:187], v[126:129]
	v_mfma_f32_16x16x32_bf16 v[122:125], v[156:159], v[184:187], v[122:125]
	v_mfma_f32_16x16x32_bf16 v[110:113], v[148:151], v[196:199], v[110:113]
	v_mfma_f32_16x16x32_bf16 v[106:109], v[156:159], v[196:199], v[106:109]
	v_mfma_f32_16x16x32_bf16 v[94:97], v[148:151], v[214:217], v[94:97]
	v_mfma_f32_16x16x32_bf16 v[90:93], v[156:159], v[214:217], v[90:93]
	v_mfma_f32_16x16x32_bf16 v[78:81], v[148:151], v[222:225], v[78:81]
	v_mfma_f32_16x16x32_bf16 v[74:77], v[156:159], v[222:225], v[74:77]
	v_mfma_f32_16x16x32_bf16 v[118:121], v[160:163], v[176:179], v[118:121]
	v_mfma_f32_16x16x32_bf16 v[114:117], v[168:171], v[176:179], v[114:117]
	v_mfma_f32_16x16x32_bf16 v[102:105], v[160:163], v[188:191], v[102:105]
	v_mfma_f32_16x16x32_bf16 v[98:101], v[168:171], v[188:191], v[98:101]
	v_mfma_f32_16x16x32_bf16 v[86:89], v[160:163], v[210:213], v[86:89]
	v_mfma_f32_16x16x32_bf16 v[82:85], v[168:171], v[210:213], v[82:85]
	v_mfma_f32_16x16x32_bf16 v[70:73], v[160:163], v[218:221], v[70:73]
	v_mfma_f32_16x16x32_bf16 v[66:69], v[168:171], v[218:221], v[66:69]
	v_mfma_f32_16x16x32_bf16 v[118:121], v[164:167], v[184:187], v[118:121]
	v_mfma_f32_16x16x32_bf16 v[114:117], v[172:175], v[184:187], v[114:117]
	v_mfma_f32_16x16x32_bf16 v[102:105], v[164:167], v[196:199], v[102:105]
	v_mfma_f32_16x16x32_bf16 v[98:101], v[172:175], v[196:199], v[98:101]
	v_mfma_f32_16x16x32_bf16 v[86:89], v[164:167], v[214:217], v[86:89]
	v_mfma_f32_16x16x32_bf16 v[82:85], v[172:175], v[214:217], v[82:85]
	v_mfma_f32_16x16x32_bf16 v[70:73], v[164:167], v[222:225], v[70:73]
	v_mfma_f32_16x16x32_bf16 v[66:69], v[172:175], v[222:225], v[66:69]
	s_barrier
	s_add_i32 s36, s45, s50
	v_lshl_add_u64 v[180:181], v[180:181], 0, s[22:23]
	s_mov_b32 m0, s36
	ds_read_b128 v[176:179], v147 offset:49152
	ds_read_b128 v[184:187], v147 offset:50176
	ds_read_b128 v[188:191], v147 offset:51200
	ds_read_b128 v[196:199], v147 offset:52224
	ds_read_b128 v[210:213], v147 offset:53248
	ds_read_b128 v[214:217], v147 offset:54272
	ds_read_b128 v[218:221], v147 offset:55296
	ds_read_b128 v[222:225], v147 offset:56320
	global_load_lds_dwordx4 v[180:181], off
	s_add_i32 m0, s36, 0x2000
	s_add_u32 s30, s30, 0x100080
	v_lshl_add_u64 v[180:181], v[192:193], 0, s[22:23]
	s_addc_u32 s31, s31, 0
	s_add_i32 s36, s59, s50
	global_load_lds_dwordx4 v[180:181], off
	v_lshl_add_u64 v[180:181], s[30:31], 0, v[0:1]
	s_mov_b32 m0, s36
	s_nop 0
	global_load_lds_dwordx4 v[180:181], off
	v_lshl_add_u64 v[180:181], s[30:31], 0, v[130:131]
	s_add_i32 m0, s36, 0x2000
	s_nop 0
	global_load_lds_dwordx4 v[180:181], off
	v_lshl_add_u64 v[180:181], v[202:203], 0, s[22:23]
	s_mov_b32 m0, s56
	s_nop 0
	global_load_lds_dwordx4 v[180:181], off
	v_lshl_add_u64 v[180:181], v[226:227], 0, s[22:23]
	s_mov_b32 m0, s57
	s_nop 0
	global_load_lds_dwordx4 v[180:181], off
	s_waitcnt vmcnt(8)
	s_waitcnt lgkmcnt(0)
	s_barrier
	s_waitcnt lgkmcnt(0)
	v_mfma_f32_16x16x32_bf16 v[62:65], v[140:143], v[176:179], v[62:65]
	v_mfma_f32_16x16x32_bf16 v[58:61], v[152:155], v[176:179], v[58:61]
	v_mfma_f32_16x16x32_bf16 v[46:49], v[140:143], v[188:191], v[46:49]
	v_mfma_f32_16x16x32_bf16 v[42:45], v[152:155], v[188:191], v[42:45]
	v_mfma_f32_16x16x32_bf16 v[30:33], v[140:143], v[210:213], v[30:33]
	v_mfma_f32_16x16x32_bf16 v[26:29], v[152:155], v[210:213], v[26:29]
	v_mfma_f32_16x16x32_bf16 v[14:17], v[140:143], v[218:221], v[14:17]
	v_mfma_f32_16x16x32_bf16 v[10:13], v[152:155], v[218:221], v[10:13]
	v_mfma_f32_16x16x32_bf16 v[62:65], v[148:151], v[184:187], v[62:65]
	v_mfma_f32_16x16x32_bf16 v[58:61], v[156:159], v[184:187], v[58:61]
	v_mfma_f32_16x16x32_bf16 v[46:49], v[148:151], v[196:199], v[46:49]
	v_mfma_f32_16x16x32_bf16 v[42:45], v[156:159], v[196:199], v[42:45]
	v_mfma_f32_16x16x32_bf16 v[30:33], v[148:151], v[214:217], v[30:33]
	v_mfma_f32_16x16x32_bf16 v[26:29], v[156:159], v[214:217], v[26:29]
	v_mfma_f32_16x16x32_bf16 v[14:17], v[148:151], v[222:225], v[14:17]
	v_mfma_f32_16x16x32_bf16 v[10:13], v[156:159], v[222:225], v[10:13]
	v_mfma_f32_16x16x32_bf16 v[54:57], v[160:163], v[176:179], v[54:57]
	v_mfma_f32_16x16x32_bf16 v[50:53], v[168:171], v[176:179], v[50:53]
	v_mfma_f32_16x16x32_bf16 v[38:41], v[160:163], v[188:191], v[38:41]
	v_mfma_f32_16x16x32_bf16 v[34:37], v[168:171], v[188:191], v[34:37]
	v_mfma_f32_16x16x32_bf16 v[22:25], v[160:163], v[210:213], v[22:25]
	v_mfma_f32_16x16x32_bf16 v[18:21], v[168:171], v[210:213], v[18:21]
	v_mfma_f32_16x16x32_bf16 v[6:9], v[160:163], v[218:221], v[6:9]
	v_mfma_f32_16x16x32_bf16 v[2:5], v[168:171], v[218:221], v[2:5]
	v_mfma_f32_16x16x32_bf16 v[54:57], v[164:167], v[184:187], v[54:57]
	v_mfma_f32_16x16x32_bf16 v[50:53], v[172:175], v[184:187], v[50:53]
	v_mfma_f32_16x16x32_bf16 v[38:41], v[164:167], v[196:199], v[38:41]
	v_mfma_f32_16x16x32_bf16 v[34:37], v[172:175], v[196:199], v[34:37]
	v_mfma_f32_16x16x32_bf16 v[22:25], v[164:167], v[214:217], v[22:25]
	v_mfma_f32_16x16x32_bf16 v[18:21], v[172:175], v[214:217], v[18:21]
	v_mfma_f32_16x16x32_bf16 v[6:9], v[164:167], v[222:225], v[6:9]
	v_mfma_f32_16x16x32_bf16 v[2:5], v[172:175], v[222:225], v[2:5]
	s_barrier
	s_add_i32 s35, s35, 2
	s_add_u32 s12, s12, 0x100
	s_addc_u32 s13, s13, 0
	s_add_u32 s26, s26, 0x100
	s_addc_u32 s28, s28, 0
	s_cmp_gt_u32 s35, 61
	s_cbranch_scc0 .LBB0_864
	s_setprio 0
	s_and_b64 vcc, exec, s[20:21]
	s_cbranch_vccz .LBB0_867
	s_barrier

.LBB0_955:
	v_mov_b32_e32 v125, 0
	s_andn2_b64 vcc, exec, s[20:21]
	v_mov_b32_e32 v124, v125
	v_mov_b32_e32 v123, v125
	v_mov_b32_e32 v122, v125
	v_mov_b32_e32 v129, v125
	v_mov_b32_e32 v128, v125
	v_mov_b32_e32 v127, v125
	v_mov_b32_e32 v126, v125
	v_mov_b32_e32 v113, v125
	v_mov_b32_e32 v112, v125
	v_mov_b32_e32 v111, v125
	v_mov_b32_e32 v110, v125
	v_mov_b32_e32 v109, v125
	v_mov_b32_e32 v108, v125
	v_mov_b32_e32 v107, v125
	v_mov_b32_e32 v106, v125
	v_mov_b32_e32 v97, v125
	v_mov_b32_e32 v96, v125
	v_mov_b32_e32 v95, v125
	v_mov_b32_e32 v94, v125
	v_mov_b32_e32 v93, v125
	v_mov_b32_e32 v92, v125
	v_mov_b32_e32 v91, v125
	v_mov_b32_e32 v90, v125
	v_mov_b32_e32 v81, v125
	v_mov_b32_e32 v80, v125
	v_mov_b32_e32 v79, v125
	v_mov_b32_e32 v78, v125
	v_mov_b32_e32 v77, v125
	v_mov_b32_e32 v76, v125
	v_mov_b32_e32 v75, v125
	v_mov_b32_e32 v74, v125
	v_mov_b32_e32 v121, v125
	v_mov_b32_e32 v120, v125
	v_mov_b32_e32 v119, v125
	v_mov_b32_e32 v118, v125
	v_mov_b32_e32 v117, v125
	v_mov_b32_e32 v116, v125
	v_mov_b32_e32 v115, v125
	v_mov_b32_e32 v114, v125
	v_mov_b32_e32 v105, v125
	v_mov_b32_e32 v104, v125
	v_mov_b32_e32 v103, v125
	v_mov_b32_e32 v102, v125
	v_mov_b32_e32 v101, v125
	v_mov_b32_e32 v100, v125
	v_mov_b32_e32 v99, v125
	v_mov_b32_e32 v98, v125
	v_mov_b32_e32 v89, v125
	v_mov_b32_e32 v88, v125
	v_mov_b32_e32 v87, v125
	v_mov_b32_e32 v86, v125
	v_mov_b32_e32 v85, v125
	v_mov_b32_e32 v84, v125
	v_mov_b32_e32 v83, v125
	v_mov_b32_e32 v82, v125
	v_mov_b32_e32 v73, v125
	v_mov_b32_e32 v72, v125
	v_mov_b32_e32 v71, v125
	v_mov_b32_e32 v70, v125
	v_mov_b32_e32 v69, v125
	v_mov_b32_e32 v68, v125
	v_mov_b32_e32 v67, v125
	v_mov_b32_e32 v66, v125
	v_mov_b32_e32 v65, v125
	v_mov_b32_e32 v64, v125
	v_mov_b32_e32 v63, v125
	v_mov_b32_e32 v62, v125
	v_mov_b32_e32 v61, v125
	v_mov_b32_e32 v60, v125
	v_mov_b32_e32 v59, v125
	v_mov_b32_e32 v58, v125
	v_mov_b32_e32 v49, v125
	v_mov_b32_e32 v48, v125
	v_mov_b32_e32 v47, v125
	v_mov_b32_e32 v46, v125
	v_mov_b32_e32 v45, v125
	v_mov_b32_e32 v44, v125
	v_mov_b32_e32 v43, v125
	v_mov_b32_e32 v42, v125
	v_mov_b32_e32 v33, v125
	v_mov_b32_e32 v32, v125
	v_mov_b32_e32 v31, v125
	v_mov_b32_e32 v30, v125
	v_mov_b32_e32 v29, v125
	v_mov_b32_e32 v28, v125
	v_mov_b32_e32 v27, v125
	v_mov_b32_e32 v26, v125
	v_mov_b32_e32 v17, v125
	v_mov_b32_e32 v16, v125
	v_mov_b32_e32 v15, v125
	v_mov_b32_e32 v14, v125
	v_mov_b32_e32 v13, v125
	v_mov_b32_e32 v12, v125
	v_mov_b32_e32 v11, v125
	v_mov_b32_e32 v10, v125
	v_mov_b32_e32 v57, v125
	v_mov_b32_e32 v56, v125
	v_mov_b32_e32 v55, v125
	v_mov_b32_e32 v54, v125
	v_mov_b32_e32 v53, v125
	v_mov_b32_e32 v52, v125
	v_mov_b32_e32 v51, v125
	v_mov_b32_e32 v50, v125
	v_mov_b32_e32 v41, v125
	v_mov_b32_e32 v40, v125
	v_mov_b32_e32 v39, v125
	v_mov_b32_e32 v38, v125
	v_mov_b32_e32 v37, v125
	v_mov_b32_e32 v36, v125
	v_mov_b32_e32 v35, v125
	v_mov_b32_e32 v34, v125
	v_mov_b32_e32 v25, v125
	v_mov_b32_e32 v24, v125
	v_mov_b32_e32 v23, v125
	v_mov_b32_e32 v22, v125
	v_mov_b32_e32 v21, v125
	v_mov_b32_e32 v20, v125
	v_mov_b32_e32 v19, v125
	v_mov_b32_e32 v18, v125
	v_mov_b32_e32 v9, v125
	v_mov_b32_e32 v8, v125
	v_mov_b32_e32 v7, v125
	v_mov_b32_e32 v6, v125
	v_mov_b32_e32 v5, v125
	v_mov_b32_e32 v4, v125
	v_mov_b32_e32 v3, v125
	v_mov_b32_e32 v2, v125
	s_cbranch_vccnz .LBB0_958
	s_add_u32 s36, s36, 0x80
	s_addc_u32 s37, s37, 0
	s_add_u32 s50, s40, 0x100
	s_addc_u32 s51, s41, 0
	s_mov_b32 s40, 0
	v_mov_b64_e32 v[2:3], 0
	v_mov_b64_e32 v[4:5], 0
	v_mov_b64_e32 v[6:7], 0
	v_mov_b64_e32 v[8:9], 0
	v_mov_b64_e32 v[10:11], 0
	v_mov_b64_e32 v[12:13], 0
	v_mov_b64_e32 v[14:15], 0
	v_mov_b64_e32 v[16:17], 0
	v_mov_b64_e32 v[18:19], 0
	v_mov_b64_e32 v[20:21], 0
	v_mov_b64_e32 v[22:23], 0
	v_mov_b64_e32 v[24:25], 0
	v_mov_b64_e32 v[26:27], 0
	v_mov_b64_e32 v[28:29], 0
	v_mov_b64_e32 v[30:31], 0
	v_mov_b64_e32 v[32:33], 0
	v_mov_b64_e32 v[34:35], 0
	v_mov_b64_e32 v[36:37], 0
	v_mov_b64_e32 v[38:39], 0
	v_mov_b64_e32 v[40:41], 0
	v_mov_b64_e32 v[42:43], 0
	v_mov_b64_e32 v[44:45], 0
	v_mov_b64_e32 v[46:47], 0
	v_mov_b64_e32 v[48:49], 0
	v_mov_b64_e32 v[50:51], 0
	v_mov_b64_e32 v[52:53], 0
	v_mov_b64_e32 v[54:55], 0
	v_mov_b64_e32 v[56:57], 0
	v_mov_b64_e32 v[58:59], 0
	v_mov_b64_e32 v[60:61], 0
	v_mov_b64_e32 v[62:63], 0
	v_mov_b64_e32 v[64:65], 0
	v_mov_b64_e32 v[66:67], 0
	v_mov_b64_e32 v[68:69], 0
	v_mov_b64_e32 v[70:71], 0
	v_mov_b64_e32 v[72:73], 0
	v_mov_b64_e32 v[74:75], 0
	v_mov_b64_e32 v[76:77], 0
	v_mov_b64_e32 v[78:79], 0
	v_mov_b64_e32 v[80:81], 0
	v_mov_b64_e32 v[82:83], 0
	v_mov_b64_e32 v[84:85], 0
	v_mov_b64_e32 v[86:87], 0
	v_mov_b64_e32 v[88:89], 0
	v_mov_b64_e32 v[90:91], 0
	v_mov_b64_e32 v[92:93], 0
	v_mov_b64_e32 v[94:95], 0
	v_mov_b64_e32 v[96:97], 0
	v_mov_b64_e32 v[98:99], 0
	v_mov_b64_e32 v[100:101], 0
	v_mov_b64_e32 v[102:103], 0
	v_mov_b64_e32 v[104:105], 0
	v_mov_b64_e32 v[106:107], 0
	v_mov_b64_e32 v[108:109], 0
	v_mov_b64_e32 v[110:111], 0
	v_mov_b64_e32 v[112:113], 0
	v_mov_b64_e32 v[114:115], 0
	v_mov_b64_e32 v[116:117], 0
	v_mov_b64_e32 v[118:119], 0
	v_mov_b64_e32 v[120:121], 0
	v_mov_b64_e32 v[122:123], 0
	v_mov_b64_e32 v[124:125], 0
	v_mov_b64_e32 v[126:127], 0
	v_mov_b64_e32 v[128:129], 0
	s_cmp_lt_u32 s32, 0x100
	s_cbranch_scc1 .Lsprio_4
	s_setprio 1
.Lsprio_4:
.LBB0_957:
	s_add_i32 s52, s40, 2
	s_add_u32 s53, s36, 0x80
	s_addc_u32 s41, s37, 0
	s_add_i32 s56, 0, 0x10000
	s_cmp_eq_u32 s44, s40
	s_cselect_b32 s41, s7, s41
	s_cselect_b32 s40, s6, s53
	s_cselect_b32 s55, s35, s51
	s_cselect_b32 s54, s34, s50
	s_add_i32 s53, 0, 0x14000
	v_add_u32_e32 v154, s56, v140
	v_add_u32_e32 v170, s53, v140
	ds_read_b128 v[142:145], v154
	ds_read_b128 v[146:149], v154 offset:1024
	ds_read_b128 v[150:153], v154 offset:2048
	ds_read_b128 v[154:157], v154 offset:3072
	ds_read_b128 v[158:161], v170
	ds_read_b128 v[162:165], v170 offset:1024
	ds_read_b128 v[166:169], v170 offset:2048
	ds_read_b128 v[170:173], v170 offset:3072
	v_lshl_add_u64 v[192:193], s[36:37], 0, v[136:137]
	s_add_i32 m0, s18, 0xc000
	ds_read_b128 v[174:177], v141
	ds_read_b128 v[178:181], v141 offset:1024
	ds_read_b128 v[184:187], v141 offset:2048
	ds_read_b128 v[188:191], v141 offset:3072
	ds_read_b128 v[196:199], v141 offset:4096
	ds_read_b128 v[210:213], v141 offset:5120
	ds_read_b128 v[214:217], v141 offset:6144
	ds_read_b128 v[218:221], v141 offset:7168
	global_load_lds_dwordx4 v[192:193], off
	v_lshl_add_u64 v[192:193], s[36:37], 0, v[138:139]
	s_add_i32 m0, s18, 0xe000
	s_nop 0
	global_load_lds_dwordx4 v[192:193], off
	s_waitcnt vmcnt(8)
	s_waitcnt lgkmcnt(0)
	s_barrier
	s_waitcnt lgkmcnt(0)
	v_mfma_f32_16x16x32_bf16 v[122:125], v[142:145], v[174:177], v[122:125]
	v_mfma_f32_16x16x32_bf16 v[126:129], v[150:153], v[174:177], v[126:129]
	v_mfma_f32_16x16x32_bf16 v[110:113], v[142:145], v[184:187], v[110:113]
	v_mfma_f32_16x16x32_bf16 v[106:109], v[150:153], v[184:187], v[106:109]
	v_mfma_f32_16x16x32_bf16 v[94:97], v[142:145], v[196:199], v[94:97]
	v_mfma_f32_16x16x32_bf16 v[90:93], v[150:153], v[196:199], v[90:93]
	v_mfma_f32_16x16x32_bf16 v[78:81], v[142:145], v[214:217], v[78:81]
	v_mfma_f32_16x16x32_bf16 v[74:77], v[150:153], v[214:217], v[74:77]
	v_mfma_f32_16x16x32_bf16 v[122:125], v[146:149], v[178:181], v[122:125]
	v_mfma_f32_16x16x32_bf16 v[126:129], v[154:157], v[178:181], v[126:129]
	v_mfma_f32_16x16x32_bf16 v[110:113], v[146:149], v[188:191], v[110:113]
	v_mfma_f32_16x16x32_bf16 v[106:109], v[154:157], v[188:191], v[106:109]
	v_mfma_f32_16x16x32_bf16 v[94:97], v[146:149], v[210:213], v[94:97]
	v_mfma_f32_16x16x32_bf16 v[90:93], v[154:157], v[210:213], v[90:93]
	v_mfma_f32_16x16x32_bf16 v[78:81], v[146:149], v[218:221], v[78:81]
	v_mfma_f32_16x16x32_bf16 v[74:77], v[154:157], v[218:221], v[74:77]
	v_mfma_f32_16x16x32_bf16 v[118:121], v[158:161], v[174:177], v[118:121]
	v_mfma_f32_16x16x32_bf16 v[114:117], v[166:169], v[174:177], v[114:117]
	v_mfma_f32_16x16x32_bf16 v[102:105], v[158:161], v[184:187], v[102:105]
	v_mfma_f32_16x16x32_bf16 v[98:101], v[166:169], v[184:187], v[98:101]
	v_mfma_f32_16x16x32_bf16 v[86:89], v[158:161], v[196:199], v[86:89]
	v_mfma_f32_16x16x32_bf16 v[82:85], v[166:169], v[196:199], v[82:85]
	v_mfma_f32_16x16x32_bf16 v[70:73], v[158:161], v[214:217], v[70:73]
	v_mfma_f32_16x16x32_bf16 v[66:69], v[166:169], v[214:217], v[66:69]
	v_mfma_f32_16x16x32_bf16 v[118:121], v[162:165], v[178:181], v[118:121]
	v_mfma_f32_16x16x32_bf16 v[114:117], v[170:173], v[178:181], v[114:117]
	v_mfma_f32_16x16x32_bf16 v[102:105], v[162:165], v[188:191], v[102:105]
	v_mfma_f32_16x16x32_bf16 v[98:101], v[170:173], v[188:191], v[98:101]
	v_mfma_f32_16x16x32_bf16 v[86:89], v[162:165], v[210:213], v[86:89]
	v_mfma_f32_16x16x32_bf16 v[82:85], v[170:173], v[210:213], v[82:85]
	v_mfma_f32_16x16x32_bf16 v[70:73], v[162:165], v[218:221], v[70:73]
	v_mfma_f32_16x16x32_bf16 v[66:69], v[170:173], v[218:221], v[66:69]
	s_barrier
	s_add_i32 s56, s56, s17
	v_lshl_add_u64 v[192:193], s[54:55], 0, v[0:1]
	s_mov_b32 m0, s56
	ds_read_b128 v[174:177], v141 offset:16384
	ds_read_b128 v[178:181], v141 offset:17408
	ds_read_b128 v[184:187], v141 offset:18432
	ds_read_b128 v[188:191], v141 offset:19456
	ds_read_b128 v[196:199], v141 offset:20480
	ds_read_b128 v[210:213], v141 offset:21504
	ds_read_b128 v[214:217], v141 offset:22528
	ds_read_b128 v[218:221], v141 offset:23552
	global_load_lds_dwordx4 v[192:193], off
	s_add_i32 m0, s56, 0x2000
	v_lshl_add_u64 v[202:203], s[54:55], 0, v[130:131]
	s_add_u32 s54, s54, s10
	s_addc_u32 s55, s55, s11
	s_add_i32 s53, s53, s17
	global_load_lds_dwordx4 v[202:203], off
	v_lshl_add_u64 v[222:223], s[54:55], 0, v[0:1]
	s_mov_b32 m0, s53
	v_lshl_add_u64 v[224:225], s[54:55], 0, v[130:131]
	global_load_lds_dwordx4 v[222:223], off
	s_add_i32 m0, s53, 0x2000
	v_lshl_add_u64 v[226:227], s[40:41], 0, v[134:135]
	global_load_lds_dwordx4 v[224:225], off
	s_mov_b32 m0, s18
	v_lshl_add_u64 v[228:229], s[40:41], 0, v[132:133]
	global_load_lds_dwordx4 v[226:227], off
	s_mov_b32 m0, s19
	s_nop 0
	global_load_lds_dwordx4 v[228:229], off
	s_waitcnt vmcnt(8)
	s_waitcnt lgkmcnt(0)
	s_barrier
	s_waitcnt lgkmcnt(0)
	v_mfma_f32_16x16x32_bf16 v[62:65], v[142:145], v[174:177], v[62:65]
	v_mfma_f32_16x16x32_bf16 v[58:61], v[150:153], v[174:177], v[58:61]
	v_mfma_f32_16x16x32_bf16 v[46:49], v[142:145], v[184:187], v[46:49]
	v_mfma_f32_16x16x32_bf16 v[42:45], v[150:153], v[184:187], v[42:45]
	v_mfma_f32_16x16x32_bf16 v[30:33], v[142:145], v[196:199], v[30:33]
	v_mfma_f32_16x16x32_bf16 v[26:29], v[150:153], v[196:199], v[26:29]
	v_mfma_f32_16x16x32_bf16 v[14:17], v[142:145], v[214:217], v[14:17]
	v_mfma_f32_16x16x32_bf16 v[10:13], v[150:153], v[214:217], v[10:13]
	v_mfma_f32_16x16x32_bf16 v[62:65], v[146:149], v[178:181], v[62:65]
	v_mfma_f32_16x16x32_bf16 v[58:61], v[154:157], v[178:181], v[58:61]
	v_mfma_f32_16x16x32_bf16 v[46:49], v[146:149], v[188:191], v[46:49]
	v_mfma_f32_16x16x32_bf16 v[42:45], v[154:157], v[188:191], v[42:45]
	v_mfma_f32_16x16x32_bf16 v[30:33], v[146:149], v[210:213], v[30:33]
	v_mfma_f32_16x16x32_bf16 v[26:29], v[154:157], v[210:213], v[26:29]
	v_mfma_f32_16x16x32_bf16 v[14:17], v[146:149], v[218:221], v[14:17]
	v_mfma_f32_16x16x32_bf16 v[10:13], v[154:157], v[218:221], v[10:13]
	v_mfma_f32_16x16x32_bf16 v[54:57], v[158:161], v[174:177], v[54:57]
	v_mfma_f32_16x16x32_bf16 v[50:53], v[166:169], v[174:177], v[50:53]
	v_mfma_f32_16x16x32_bf16 v[38:41], v[158:161], v[184:187], v[38:41]
	v_mfma_f32_16x16x32_bf16 v[34:37], v[166:169], v[184:187], v[34:37]
	v_mfma_f32_16x16x32_bf16 v[22:25], v[158:161], v[196:199], v[22:25]
	v_mfma_f32_16x16x32_bf16 v[18:21], v[166:169], v[196:199], v[18:21]
	v_mfma_f32_16x16x32_bf16 v[6:9], v[158:161], v[214:217], v[6:9]
	v_mfma_f32_16x16x32_bf16 v[2:5], v[166:169], v[214:217], v[2:5]
	v_mfma_f32_16x16x32_bf16 v[54:57], v[162:165], v[178:181], v[54:57]
	v_mfma_f32_16x16x32_bf16 v[50:53], v[170:173], v[178:181], v[50:53]
	v_mfma_f32_16x16x32_bf16 v[38:41], v[162:165], v[188:191], v[38:41]
	v_mfma_f32_16x16x32_bf16 v[34:37], v[170:173], v[188:191], v[34:37]
	v_mfma_f32_16x16x32_bf16 v[22:25], v[162:165], v[210:213], v[22:25]
	v_mfma_f32_16x16x32_bf16 v[18:21], v[170:173], v[210:213], v[18:21]
	v_mfma_f32_16x16x32_bf16 v[6:9], v[162:165], v[218:221], v[6:9]
	v_mfma_f32_16x16x32_bf16 v[2:5], v[170:173], v[218:221], v[2:5]
	s_barrier
	s_add_i32 s53, 0, 0x18000
	s_add_i32 s54, 0, 0x1c000
	v_add_u32_e32 v154, s53, v140
	v_add_u32_e32 v170, s54, v140
	ds_read_b128 v[142:145], v154
	ds_read_b128 v[146:149], v154 offset:1024
	ds_read_b128 v[150:153], v154 offset:2048
	ds_read_b128 v[154:157], v154 offset:3072
	ds_read_b128 v[158:161], v170
	ds_read_b128 v[162:165], v170 offset:1024
	ds_read_b128 v[166:169], v170 offset:2048
	ds_read_b128 v[170:173], v170 offset:3072
	s_add_u32 s40, s40, s10
	s_addc_u32 s41, s41, s11
	s_mov_b32 m0, s24
	v_lshl_add_u64 v[230:231], s[40:41], 0, v[134:135]
	ds_read_b128 v[174:177], v141 offset:32768
	ds_read_b128 v[178:181], v141 offset:33792
	ds_read_b128 v[184:187], v141 offset:34816
	ds_read_b128 v[188:191], v141 offset:35840
	ds_read_b128 v[196:199], v141 offset:36864
	ds_read_b128 v[210:213], v141 offset:37888
	ds_read_b128 v[214:217], v141 offset:38912
	ds_read_b128 v[218:221], v141 offset:39936
	global_load_lds_dwordx4 v[230:231], off
	v_lshl_add_u64 v[230:231], s[40:41], 0, v[132:133]
	s_mov_b32 m0, s25
	s_nop 0
	global_load_lds_dwordx4 v[230:231], off
	s_waitcnt vmcnt(8)
	s_waitcnt lgkmcnt(0)
	s_barrier
	s_waitcnt lgkmcnt(0)
	v_mfma_f32_16x16x32_bf16 v[122:125], v[142:145], v[174:177], v[122:125]
	v_mfma_f32_16x16x32_bf16 v[126:129], v[150:153], v[174:177], v[126:129]
	v_mfma_f32_16x16x32_bf16 v[110:113], v[142:145], v[184:187], v[110:113]
	v_mfma_f32_16x16x32_bf16 v[106:109], v[150:153], v[184:187], v[106:109]
	v_mfma_f32_16x16x32_bf16 v[94:97], v[142:145], v[196:199], v[94:97]
	v_mfma_f32_16x16x32_bf16 v[90:93], v[150:153], v[196:199], v[90:93]
	v_mfma_f32_16x16x32_bf16 v[78:81], v[142:145], v[214:217], v[78:81]
	v_mfma_f32_16x16x32_bf16 v[74:77], v[150:153], v[214:217], v[74:77]
	v_mfma_f32_16x16x32_bf16 v[122:125], v[146:149], v[178:181], v[122:125]
	v_mfma_f32_16x16x32_bf16 v[126:129], v[154:157], v[178:181], v[126:129]
	v_mfma_f32_16x16x32_bf16 v[110:113], v[146:149], v[188:191], v[110:113]
	v_mfma_f32_16x16x32_bf16 v[106:109], v[154:157], v[188:191], v[106:109]
	v_mfma_f32_16x16x32_bf16 v[94:97], v[146:149], v[210:213], v[94:97]
	v_mfma_f32_16x16x32_bf16 v[90:93], v[154:157], v[210:213], v[90:93]
	v_mfma_f32_16x16x32_bf16 v[78:81], v[146:149], v[218:221], v[78:81]
	v_mfma_f32_16x16x32_bf16 v[74:77], v[154:157], v[218:221], v[74:77]
	v_mfma_f32_16x16x32_bf16 v[118:121], v[158:161], v[174:177], v[118:121]
	v_mfma_f32_16x16x32_bf16 v[114:117], v[166:169], v[174:177], v[114:117]
	v_mfma_f32_16x16x32_bf16 v[102:105], v[158:161], v[184:187], v[102:105]
	v_mfma_f32_16x16x32_bf16 v[98:101], v[166:169], v[184:187], v[98:101]
	v_mfma_f32_16x16x32_bf16 v[86:89], v[158:161], v[196:199], v[86:89]
	v_mfma_f32_16x16x32_bf16 v[82:85], v[166:169], v[196:199], v[82:85]
	v_mfma_f32_16x16x32_bf16 v[70:73], v[158:161], v[214:217], v[70:73]
	v_mfma_f32_16x16x32_bf16 v[66:69], v[166:169], v[214:217], v[66:69]
	v_mfma_f32_16x16x32_bf16 v[118:121], v[162:165], v[178:181], v[118:121]
	v_mfma_f32_16x16x32_bf16 v[114:117], v[170:173], v[178:181], v[114:117]
	v_mfma_f32_16x16x32_bf16 v[102:105], v[162:165], v[188:191], v[102:105]
	v_mfma_f32_16x16x32_bf16 v[98:101], v[170:173], v[188:191], v[98:101]
	v_mfma_f32_16x16x32_bf16 v[86:89], v[162:165], v[210:213], v[86:89]
	v_mfma_f32_16x16x32_bf16 v[82:85], v[170:173], v[210:213], v[82:85]
	v_mfma_f32_16x16x32_bf16 v[70:73], v[162:165], v[218:221], v[70:73]
	v_mfma_f32_16x16x32_bf16 v[66:69], v[170:173], v[218:221], v[66:69]
	s_barrier
	s_add_i32 s40, s53, s17
	v_lshl_add_u64 v[192:193], v[192:193], 0, s[22:23]
	s_mov_b32 m0, s40
	ds_read_b128 v[174:177], v141 offset:49152
	ds_read_b128 v[178:181], v141 offset:50176
	ds_read_b128 v[184:187], v141 offset:51200
	ds_read_b128 v[188:191], v141 offset:52224
	ds_read_b128 v[196:199], v141 offset:53248
	ds_read_b128 v[210:213], v141 offset:54272
	ds_read_b128 v[214:217], v141 offset:55296
	ds_read_b128 v[218:221], v141 offset:56320
	global_load_lds_dwordx4 v[192:193], off
	v_lshl_add_u64 v[192:193], v[202:203], 0, s[22:23]
	s_add_i32 m0, s40, 0x2000
	s_add_i32 s40, s54, s17
	global_load_lds_dwordx4 v[192:193], off
	v_lshl_add_u64 v[192:193], v[222:223], 0, s[22:23]
	s_mov_b32 m0, s40
	s_nop 0
	global_load_lds_dwordx4 v[192:193], off
	v_lshl_add_u64 v[192:193], v[224:225], 0, s[22:23]
	s_add_i32 m0, s40, 0x2000
	s_nop 0
	global_load_lds_dwordx4 v[192:193], off
	v_lshl_add_u64 v[192:193], v[226:227], 0, s[22:23]
	s_mov_b32 m0, s42
	s_nop 0
	global_load_lds_dwordx4 v[192:193], off
	v_lshl_add_u64 v[192:193], v[228:229], 0, s[22:23]
	s_mov_b32 m0, s43
	s_nop 0
	global_load_lds_dwordx4 v[192:193], off
	s_waitcnt vmcnt(8)
	s_waitcnt lgkmcnt(0)
	s_barrier
	s_waitcnt lgkmcnt(0)
	v_mfma_f32_16x16x32_bf16 v[62:65], v[142:145], v[174:177], v[62:65]
	v_mfma_f32_16x16x32_bf16 v[58:61], v[150:153], v[174:177], v[58:61]
	v_mfma_f32_16x16x32_bf16 v[46:49], v[142:145], v[184:187], v[46:49]
	v_mfma_f32_16x16x32_bf16 v[42:45], v[150:153], v[184:187], v[42:45]
	v_mfma_f32_16x16x32_bf16 v[30:33], v[142:145], v[196:199], v[30:33]
	v_mfma_f32_16x16x32_bf16 v[26:29], v[150:153], v[196:199], v[26:29]
	v_mfma_f32_16x16x32_bf16 v[14:17], v[142:145], v[214:217], v[14:17]
	v_mfma_f32_16x16x32_bf16 v[10:13], v[150:153], v[214:217], v[10:13]
	v_mfma_f32_16x16x32_bf16 v[62:65], v[146:149], v[178:181], v[62:65]
	v_mfma_f32_16x16x32_bf16 v[58:61], v[154:157], v[178:181], v[58:61]
	v_mfma_f32_16x16x32_bf16 v[46:49], v[146:149], v[188:191], v[46:49]
	v_mfma_f32_16x16x32_bf16 v[42:45], v[154:157], v[188:191], v[42:45]
	v_mfma_f32_16x16x32_bf16 v[30:33], v[146:149], v[210:213], v[30:33]
	v_mfma_f32_16x16x32_bf16 v[26:29], v[154:157], v[210:213], v[26:29]
	v_mfma_f32_16x16x32_bf16 v[14:17], v[146:149], v[218:221], v[14:17]
	v_mfma_f32_16x16x32_bf16 v[10:13], v[154:157], v[218:221], v[10:13]
	v_mfma_f32_16x16x32_bf16 v[54:57], v[158:161], v[174:177], v[54:57]
	v_mfma_f32_16x16x32_bf16 v[50:53], v[166:169], v[174:177], v[50:53]
	v_mfma_f32_16x16x32_bf16 v[38:41], v[158:161], v[184:187], v[38:41]
	v_mfma_f32_16x16x32_bf16 v[34:37], v[166:169], v[184:187], v[34:37]
	v_mfma_f32_16x16x32_bf16 v[22:25], v[158:161], v[196:199], v[22:25]
	v_mfma_f32_16x16x32_bf16 v[18:21], v[166:169], v[196:199], v[18:21]
	v_mfma_f32_16x16x32_bf16 v[6:9], v[158:161], v[214:217], v[6:9]
	v_mfma_f32_16x16x32_bf16 v[2:5], v[166:169], v[214:217], v[2:5]
	v_mfma_f32_16x16x32_bf16 v[54:57], v[162:165], v[178:181], v[54:57]
	v_mfma_f32_16x16x32_bf16 v[50:53], v[170:173], v[178:181], v[50:53]
	v_mfma_f32_16x16x32_bf16 v[38:41], v[162:165], v[188:191], v[38:41]
	v_mfma_f32_16x16x32_bf16 v[34:37], v[170:173], v[188:191], v[34:37]
	v_mfma_f32_16x16x32_bf16 v[22:25], v[162:165], v[210:213], v[22:25]
	v_mfma_f32_16x16x32_bf16 v[18:21], v[170:173], v[210:213], v[18:21]
	v_mfma_f32_16x16x32_bf16 v[6:9], v[162:165], v[218:221], v[6:9]
	v_mfma_f32_16x16x32_bf16 v[2:5], v[170:173], v[218:221], v[2:5]
	s_barrier
	s_add_u32 s36, s36, 0x100
	s_addc_u32 s37, s37, 0
	s_add_u32 s50, s50, 0x100
	s_addc_u32 s51, s51, 0
	s_cmp_ge_i32 s52, s29
	s_mov_b32 s40, s52
	s_cbranch_scc0 .LBB0_957
	s_setprio 0

.LBB0_985:
	s_ashr_i32 s21, s20, 31
	s_lshl_b64 s[18:19], s[20:21], 19
	s_add_u32 s34, s29, s18
	s_addc_u32 s35, s44, s19
	s_and_b64 s[18:19], s[40:41], exec
	s_cselect_b32 s3, s35, s13
	s_cselect_b32 s16, s34, s12
	s_ashr_i32 s15, s14, 31
	s_lshl_b64 s[18:19], s[14:15], 19
	s_add_u32 s42, s45, s18
	s_addc_u32 s43, s46, s19
	s_and_b64 s[18:19], s[40:41], exec
	s_cselect_b32 s15, s43, s31
	s_cselect_b32 s18, s42, s30
	s_add_u32 s12, s12, 0x40080
	s_addc_u32 s13, s13, 0
	s_add_u32 s19, s30, 0x100
	s_addc_u32 s21, s31, 0
	s_mov_b32 s24, -2
	v_mov_b64_e32 v[2:3], 0
	v_mov_b64_e32 v[4:5], 0
	v_mov_b64_e32 v[6:7], 0
	v_mov_b64_e32 v[8:9], 0
	v_mov_b64_e32 v[10:11], 0
	v_mov_b64_e32 v[12:13], 0
	v_mov_b64_e32 v[14:15], 0
	v_mov_b64_e32 v[16:17], 0
	v_mov_b64_e32 v[18:19], 0
	v_mov_b64_e32 v[20:21], 0
	v_mov_b64_e32 v[22:23], 0
	v_mov_b64_e32 v[24:25], 0
	v_mov_b64_e32 v[26:27], 0
	v_mov_b64_e32 v[28:29], 0
	v_mov_b64_e32 v[30:31], 0
	v_mov_b64_e32 v[32:33], 0
	v_mov_b64_e32 v[34:35], 0
	v_mov_b64_e32 v[36:37], 0
	v_mov_b64_e32 v[38:39], 0
	v_mov_b64_e32 v[40:41], 0
	v_mov_b64_e32 v[42:43], 0
	v_mov_b64_e32 v[44:45], 0
	v_mov_b64_e32 v[46:47], 0
	v_mov_b64_e32 v[48:49], 0
	v_mov_b64_e32 v[50:51], 0
	v_mov_b64_e32 v[52:53], 0
	v_mov_b64_e32 v[54:55], 0
	v_mov_b64_e32 v[56:57], 0
	v_mov_b64_e32 v[58:59], 0
	v_mov_b64_e32 v[60:61], 0
	v_mov_b64_e32 v[62:63], 0
	v_mov_b64_e32 v[64:65], 0
	v_mov_b64_e32 v[66:67], 0
	v_mov_b64_e32 v[68:69], 0
	v_mov_b64_e32 v[70:71], 0
	v_mov_b64_e32 v[72:73], 0
	v_mov_b64_e32 v[74:75], 0
	v_mov_b64_e32 v[76:77], 0
	v_mov_b64_e32 v[78:79], 0
	v_mov_b64_e32 v[80:81], 0
	v_mov_b64_e32 v[82:83], 0
	v_mov_b64_e32 v[84:85], 0
	v_mov_b64_e32 v[86:87], 0
	v_mov_b64_e32 v[88:89], 0
	v_mov_b64_e32 v[90:91], 0
	v_mov_b64_e32 v[92:93], 0
	v_mov_b64_e32 v[94:95], 0
	v_mov_b64_e32 v[96:97], 0
	v_mov_b64_e32 v[98:99], 0
	v_mov_b64_e32 v[100:101], 0
	v_mov_b64_e32 v[102:103], 0
	v_mov_b64_e32 v[104:105], 0
	v_mov_b64_e32 v[106:107], 0
	v_mov_b64_e32 v[108:109], 0
	v_mov_b64_e32 v[110:111], 0
	v_mov_b64_e32 v[112:113], 0
	v_mov_b64_e32 v[114:115], 0
	v_mov_b64_e32 v[116:117], 0
	v_mov_b64_e32 v[118:119], 0
	v_mov_b64_e32 v[120:121], 0
	v_mov_b64_e32 v[122:123], 0
	v_mov_b64_e32 v[124:125], 0
	v_mov_b64_e32 v[126:127], 0
	v_mov_b64_e32 v[128:129], 0
	s_cmp_lt_u32 s32, 0x100
	s_cbranch_scc1 .Lsprio_5
	s_setprio 1
.Lsprio_5:
.LBB0_986:
	s_add_u32 s25, s12, 0xfffc0080
	s_addc_u32 s26, s13, -1
	s_add_i32 s28, 0, 0x10000
	s_cmp_eq_u32 s24, 12
	s_cselect_b32 s37, s3, s26
	s_cselect_b32 s36, s16, s25
	v_add_u32_e32 v144, s28, v147
	s_cselect_b32 s31, s15, s21
	s_cselect_b32 s30, s18, s19
	s_add_i32 s25, 0, 0x14000
	ds_read_b128 v[140:143], v144
	ds_read_b128 v[152:155], v144 offset:1024
	ds_read_b128 v[156:159], v144 offset:2048
	ds_read_b128 v[160:163], v144 offset:3072
	v_add_u32_e32 v144, s25, v147
	ds_read_b128 v[164:167], v144
	ds_read_b128 v[168:171], v144 offset:1024
	ds_read_b128 v[172:175], v144 offset:2048
	ds_read_b128 v[176:179], v144 offset:3072
	v_lshl_add_u64 v[144:145], s[12:13], 0, v[136:137]
	s_add_i32 m0, s47, 0xc000
	ds_read_b128 v[184:187], v150
	ds_read_b128 v[188:191], v150 offset:1024
	ds_read_b128 v[196:199], v150 offset:2048
	ds_read_b128 v[210:213], v150 offset:3072
	ds_read_b128 v[214:217], v150 offset:4096
	ds_read_b128 v[218:221], v150 offset:5120
	ds_read_b128 v[222:225], v150 offset:6144
	ds_read_b128 v[226:229], v150 offset:7168
	global_load_lds_dwordx4 v[144:145], off
	v_lshl_add_u64 v[144:145], s[12:13], 0, v[138:139]
	s_add_i32 m0, s47, 0xe000
	s_nop 0
	global_load_lds_dwordx4 v[144:145], off
	s_waitcnt vmcnt(8)
	s_waitcnt lgkmcnt(0)
	s_barrier
	s_waitcnt lgkmcnt(0)
	v_mfma_f32_16x16x32_bf16 v[126:129], v[140:143], v[184:187], v[126:129]
	v_mfma_f32_16x16x32_bf16 v[122:125], v[156:159], v[184:187], v[122:125]
	v_mfma_f32_16x16x32_bf16 v[110:113], v[140:143], v[196:199], v[110:113]
	v_mfma_f32_16x16x32_bf16 v[106:109], v[156:159], v[196:199], v[106:109]
	v_mfma_f32_16x16x32_bf16 v[94:97], v[140:143], v[214:217], v[94:97]
	v_mfma_f32_16x16x32_bf16 v[90:93], v[156:159], v[214:217], v[90:93]
	v_mfma_f32_16x16x32_bf16 v[78:81], v[140:143], v[222:225], v[78:81]
	v_mfma_f32_16x16x32_bf16 v[74:77], v[156:159], v[222:225], v[74:77]
	v_mfma_f32_16x16x32_bf16 v[126:129], v[152:155], v[188:191], v[126:129]
	v_mfma_f32_16x16x32_bf16 v[122:125], v[160:163], v[188:191], v[122:125]
	v_mfma_f32_16x16x32_bf16 v[110:113], v[152:155], v[210:213], v[110:113]
	v_mfma_f32_16x16x32_bf16 v[106:109], v[160:163], v[210:213], v[106:109]
	v_mfma_f32_16x16x32_bf16 v[94:97], v[152:155], v[218:221], v[94:97]
	v_mfma_f32_16x16x32_bf16 v[90:93], v[160:163], v[218:221], v[90:93]
	v_mfma_f32_16x16x32_bf16 v[78:81], v[152:155], v[226:229], v[78:81]
	v_mfma_f32_16x16x32_bf16 v[74:77], v[160:163], v[226:229], v[74:77]
	v_mfma_f32_16x16x32_bf16 v[118:121], v[164:167], v[184:187], v[118:121]
	v_mfma_f32_16x16x32_bf16 v[114:117], v[172:175], v[184:187], v[114:117]
	v_mfma_f32_16x16x32_bf16 v[102:105], v[164:167], v[196:199], v[102:105]
	v_mfma_f32_16x16x32_bf16 v[98:101], v[172:175], v[196:199], v[98:101]
	v_mfma_f32_16x16x32_bf16 v[86:89], v[164:167], v[214:217], v[86:89]
	v_mfma_f32_16x16x32_bf16 v[82:85], v[172:175], v[214:217], v[82:85]
	v_mfma_f32_16x16x32_bf16 v[70:73], v[164:167], v[222:225], v[70:73]
	v_mfma_f32_16x16x32_bf16 v[66:69], v[172:175], v[222:225], v[66:69]
	v_mfma_f32_16x16x32_bf16 v[118:121], v[168:171], v[188:191], v[118:121]
	v_mfma_f32_16x16x32_bf16 v[114:117], v[176:179], v[188:191], v[114:117]
	v_mfma_f32_16x16x32_bf16 v[102:105], v[168:171], v[210:213], v[102:105]
	v_mfma_f32_16x16x32_bf16 v[98:101], v[176:179], v[210:213], v[98:101]
	v_mfma_f32_16x16x32_bf16 v[86:89], v[168:171], v[218:221], v[86:89]
	v_mfma_f32_16x16x32_bf16 v[82:85], v[176:179], v[218:221], v[82:85]
	v_mfma_f32_16x16x32_bf16 v[70:73], v[168:171], v[226:229], v[70:73]
	v_mfma_f32_16x16x32_bf16 v[66:69], v[176:179], v[226:229], v[66:69]
	s_barrier
	s_add_i32 s26, s28, s17
	v_lshl_add_u64 v[144:145], s[30:31], 0, v[0:1]
	s_mov_b32 m0, s26
	ds_read_b128 v[184:187], v150 offset:16384
	ds_read_b128 v[188:191], v150 offset:17408
	ds_read_b128 v[196:199], v150 offset:18432
	ds_read_b128 v[210:213], v150 offset:19456
	ds_read_b128 v[214:217], v150 offset:20480
	ds_read_b128 v[218:221], v150 offset:21504
	ds_read_b128 v[222:225], v150 offset:22528
	ds_read_b128 v[226:229], v150 offset:23552
	global_load_lds_dwordx4 v[144:145], off
	s_add_i32 m0, s26, 0x2000
	s_add_u32 s60, s30, 0x40000
	v_lshl_add_u64 v[180:181], s[30:31], 0, v[130:131]
	s_addc_u32 s61, s31, 0
	s_add_i32 s25, s25, s17
	global_load_lds_dwordx4 v[180:181], off
	v_lshl_add_u64 v[192:193], s[60:61], 0, v[0:1]
	s_mov_b32 m0, s25
	v_lshl_add_u64 v[202:203], s[36:37], 0, v[132:133]
	global_load_lds_dwordx4 v[192:193], off
	v_lshl_add_u64 v[192:193], s[60:61], 0, v[130:131]
	s_add_i32 m0, s25, 0x2000
	s_nop 0
	global_load_lds_dwordx4 v[192:193], off
	v_lshl_add_u64 v[192:193], s[36:37], 0, v[134:135]
	s_mov_b32 m0, s47
	s_nop 0
	global_load_lds_dwordx4 v[192:193], off
	s_mov_b32 m0, s48
	s_nop 0
	global_load_lds_dwordx4 v[202:203], off
	s_waitcnt vmcnt(8)
	s_waitcnt lgkmcnt(0)
	s_barrier
	s_waitcnt lgkmcnt(0)
	v_mfma_f32_16x16x32_bf16 v[62:65], v[140:143], v[184:187], v[62:65]
	v_mfma_f32_16x16x32_bf16 v[58:61], v[156:159], v[184:187], v[58:61]
	v_mfma_f32_16x16x32_bf16 v[46:49], v[140:143], v[196:199], v[46:49]
	v_mfma_f32_16x16x32_bf16 v[42:45], v[156:159], v[196:199], v[42:45]
	v_mfma_f32_16x16x32_bf16 v[30:33], v[140:143], v[214:217], v[30:33]
	v_mfma_f32_16x16x32_bf16 v[26:29], v[156:159], v[214:217], v[26:29]
	v_mfma_f32_16x16x32_bf16 v[14:17], v[140:143], v[222:225], v[14:17]
	v_mfma_f32_16x16x32_bf16 v[10:13], v[156:159], v[222:225], v[10:13]
	v_mfma_f32_16x16x32_bf16 v[62:65], v[152:155], v[188:191], v[62:65]
	v_mfma_f32_16x16x32_bf16 v[58:61], v[160:163], v[188:191], v[58:61]
	v_mfma_f32_16x16x32_bf16 v[46:49], v[152:155], v[210:213], v[46:49]
	v_mfma_f32_16x16x32_bf16 v[42:45], v[160:163], v[210:213], v[42:45]
	v_mfma_f32_16x16x32_bf16 v[30:33], v[152:155], v[218:221], v[30:33]
	v_mfma_f32_16x16x32_bf16 v[26:29], v[160:163], v[218:221], v[26:29]
	v_mfma_f32_16x16x32_bf16 v[14:17], v[152:155], v[226:229], v[14:17]
	v_mfma_f32_16x16x32_bf16 v[10:13], v[160:163], v[226:229], v[10:13]
	v_mfma_f32_16x16x32_bf16 v[54:57], v[164:167], v[184:187], v[54:57]
	v_mfma_f32_16x16x32_bf16 v[50:53], v[172:175], v[184:187], v[50:53]
	v_mfma_f32_16x16x32_bf16 v[38:41], v[164:167], v[196:199], v[38:41]
	v_mfma_f32_16x16x32_bf16 v[34:37], v[172:175], v[196:199], v[34:37]
	v_mfma_f32_16x16x32_bf16 v[22:25], v[164:167], v[214:217], v[22:25]
	v_mfma_f32_16x16x32_bf16 v[18:21], v[172:175], v[214:217], v[18:21]
	v_mfma_f32_16x16x32_bf16 v[6:9], v[164:167], v[222:225], v[6:9]
	v_mfma_f32_16x16x32_bf16 v[2:5], v[172:175], v[222:225], v[2:5]
	v_mfma_f32_16x16x32_bf16 v[54:57], v[168:171], v[188:191], v[54:57]
	v_mfma_f32_16x16x32_bf16 v[50:53], v[176:179], v[188:191], v[50:53]
	v_mfma_f32_16x16x32_bf16 v[38:41], v[168:171], v[210:213], v[38:41]
	v_mfma_f32_16x16x32_bf16 v[34:37], v[176:179], v[210:213], v[34:37]
	v_mfma_f32_16x16x32_bf16 v[22:25], v[168:171], v[218:221], v[22:25]
	v_mfma_f32_16x16x32_bf16 v[18:21], v[176:179], v[218:221], v[18:21]
	v_mfma_f32_16x16x32_bf16 v[6:9], v[168:171], v[226:229], v[6:9]
	v_mfma_f32_16x16x32_bf16 v[2:5], v[176:179], v[226:229], v[2:5]
	s_barrier
	s_add_i32 s25, 0, 0x18000
	v_add_u32_e32 v151, s25, v147
	s_add_i32 s26, 0, 0x1c000
	ds_read_b128 v[140:143], v151
	ds_read_b128 v[152:155], v151 offset:1024
	ds_read_b128 v[156:159], v151 offset:2048
	ds_read_b128 v[160:163], v151 offset:3072
	v_add_u32_e32 v151, s26, v147
	ds_read_b128 v[164:167], v151
	ds_read_b128 v[168:171], v151 offset:1024
	ds_read_b128 v[172:175], v151 offset:2048
	ds_read_b128 v[176:179], v151 offset:3072
	s_add_u32 s36, s36, 0x40000
	s_addc_u32 s37, s37, 0
	s_mov_b32 m0, s49
	v_lshl_add_u64 v[230:231], s[36:37], 0, v[134:135]
	ds_read_b128 v[184:187], v150 offset:32768
	ds_read_b128 v[188:191], v150 offset:33792
	ds_read_b128 v[196:199], v150 offset:34816
	ds_read_b128 v[210:213], v150 offset:35840
	ds_read_b128 v[214:217], v150 offset:36864
	ds_read_b128 v[218:221], v150 offset:37888
	ds_read_b128 v[222:225], v150 offset:38912
	ds_read_b128 v[226:229], v150 offset:39936
	global_load_lds_dwordx4 v[230:231], off
	v_lshl_add_u64 v[230:231], s[36:37], 0, v[132:133]
	s_mov_b32 m0, s50
	s_nop 0
	global_load_lds_dwordx4 v[230:231], off
	s_waitcnt vmcnt(8)
	s_waitcnt lgkmcnt(0)
	s_barrier
	s_waitcnt lgkmcnt(0)
	v_mfma_f32_16x16x32_bf16 v[126:129], v[140:143], v[184:187], v[126:129]
	v_mfma_f32_16x16x32_bf16 v[122:125], v[156:159], v[184:187], v[122:125]
	v_mfma_f32_16x16x32_bf16 v[110:113], v[140:143], v[196:199], v[110:113]
	v_mfma_f32_16x16x32_bf16 v[106:109], v[156:159], v[196:199], v[106:109]
	v_mfma_f32_16x16x32_bf16 v[94:97], v[140:143], v[214:217], v[94:97]
	v_mfma_f32_16x16x32_bf16 v[90:93], v[156:159], v[214:217], v[90:93]
	v_mfma_f32_16x16x32_bf16 v[78:81], v[140:143], v[222:225], v[78:81]
	v_mfma_f32_16x16x32_bf16 v[74:77], v[156:159], v[222:225], v[74:77]
	v_mfma_f32_16x16x32_bf16 v[126:129], v[152:155], v[188:191], v[126:129]
	v_mfma_f32_16x16x32_bf16 v[122:125], v[160:163], v[188:191], v[122:125]
	v_mfma_f32_16x16x32_bf16 v[110:113], v[152:155], v[210:213], v[110:113]
	v_mfma_f32_16x16x32_bf16 v[106:109], v[160:163], v[210:213], v[106:109]
	v_mfma_f32_16x16x32_bf16 v[94:97], v[152:155], v[218:221], v[94:97]
	v_mfma_f32_16x16x32_bf16 v[90:93], v[160:163], v[218:221], v[90:93]
	v_mfma_f32_16x16x32_bf16 v[78:81], v[152:155], v[226:229], v[78:81]
	v_mfma_f32_16x16x32_bf16 v[74:77], v[160:163], v[226:229], v[74:77]
	v_mfma_f32_16x16x32_bf16 v[118:121], v[164:167], v[184:187], v[118:121]
	v_mfma_f32_16x16x32_bf16 v[114:117], v[172:175], v[184:187], v[114:117]
	v_mfma_f32_16x16x32_bf16 v[102:105], v[164:167], v[196:199], v[102:105]
	v_mfma_f32_16x16x32_bf16 v[98:101], v[172:175], v[196:199], v[98:101]
	v_mfma_f32_16x16x32_bf16 v[86:89], v[164:167], v[214:217], v[86:89]
	v_mfma_f32_16x16x32_bf16 v[82:85], v[172:175], v[214:217], v[82:85]
	v_mfma_f32_16x16x32_bf16 v[70:73], v[164:167], v[222:225], v[70:73]
	v_mfma_f32_16x16x32_bf16 v[66:69], v[172:175], v[222:225], v[66:69]
	v_mfma_f32_16x16x32_bf16 v[118:121], v[168:171], v[188:191], v[118:121]
	v_mfma_f32_16x16x32_bf16 v[114:117], v[176:179], v[188:191], v[114:117]
	v_mfma_f32_16x16x32_bf16 v[102:105], v[168:171], v[210:213], v[102:105]
	v_mfma_f32_16x16x32_bf16 v[98:101], v[176:179], v[210:213], v[98:101]
	v_mfma_f32_16x16x32_bf16 v[86:89], v[168:171], v[218:221], v[86:89]
	v_mfma_f32_16x16x32_bf16 v[82:85], v[176:179], v[218:221], v[82:85]
	v_mfma_f32_16x16x32_bf16 v[70:73], v[168:171], v[226:229], v[70:73]
	v_mfma_f32_16x16x32_bf16 v[66:69], v[176:179], v[226:229], v[66:69]
	s_barrier
	s_add_i32 s25, s25, s17
	v_lshl_add_u64 v[144:145], v[144:145], 0, s[22:23]
	s_mov_b32 m0, s25
	ds_read_b128 v[184:187], v150 offset:49152
	ds_read_b128 v[188:191], v150 offset:50176
	ds_read_b128 v[196:199], v150 offset:51200
	ds_read_b128 v[210:213], v150 offset:52224
	ds_read_b128 v[214:217], v150 offset:53248
	ds_read_b128 v[218:221], v150 offset:54272
	ds_read_b128 v[222:225], v150 offset:55296
	ds_read_b128 v[226:229], v150 offset:56320
	global_load_lds_dwordx4 v[144:145], off
	s_add_i32 m0, s25, 0x2000
	s_add_u32 s30, s30, 0x40080
	v_lshl_add_u64 v[144:145], v[180:181], 0, s[22:23]
	s_addc_u32 s31, s31, 0
	s_add_i32 s25, s26, s17
	global_load_lds_dwordx4 v[144:145], off
	v_lshl_add_u64 v[144:145], s[30:31], 0, v[0:1]
	s_mov_b32 m0, s25
	s_nop 0
	global_load_lds_dwordx4 v[144:145], off
	v_lshl_add_u64 v[144:145], s[30:31], 0, v[130:131]
	s_add_i32 m0, s25, 0x2000
	s_nop 0
	global_load_lds_dwordx4 v[144:145], off
	v_lshl_add_u64 v[144:145], v[192:193], 0, s[22:23]
	s_mov_b32 m0, s54
	s_nop 0
	global_load_lds_dwordx4 v[144:145], off
	v_lshl_add_u64 v[144:145], v[202:203], 0, s[22:23]
	s_mov_b32 m0, s55
	s_nop 0
	global_load_lds_dwordx4 v[144:145], off
	s_waitcnt vmcnt(8)
	s_waitcnt lgkmcnt(0)
	s_barrier
	s_waitcnt lgkmcnt(0)
	v_mfma_f32_16x16x32_bf16 v[62:65], v[140:143], v[184:187], v[62:65]
	v_mfma_f32_16x16x32_bf16 v[58:61], v[156:159], v[184:187], v[58:61]
	v_mfma_f32_16x16x32_bf16 v[46:49], v[140:143], v[196:199], v[46:49]
	v_mfma_f32_16x16x32_bf16 v[42:45], v[156:159], v[196:199], v[42:45]
	v_mfma_f32_16x16x32_bf16 v[30:33], v[140:143], v[214:217], v[30:33]
	v_mfma_f32_16x16x32_bf16 v[26:29], v[156:159], v[214:217], v[26:29]
	v_mfma_f32_16x16x32_bf16 v[14:17], v[140:143], v[222:225], v[14:17]
	v_mfma_f32_16x16x32_bf16 v[10:13], v[156:159], v[222:225], v[10:13]
	v_mfma_f32_16x16x32_bf16 v[62:65], v[152:155], v[188:191], v[62:65]
	v_mfma_f32_16x16x32_bf16 v[58:61], v[160:163], v[188:191], v[58:61]
	v_mfma_f32_16x16x32_bf16 v[46:49], v[152:155], v[210:213], v[46:49]
	v_mfma_f32_16x16x32_bf16 v[42:45], v[160:163], v[210:213], v[42:45]
	v_mfma_f32_16x16x32_bf16 v[30:33], v[152:155], v[218:221], v[30:33]
	v_mfma_f32_16x16x32_bf16 v[26:29], v[160:163], v[218:221], v[26:29]
	v_mfma_f32_16x16x32_bf16 v[14:17], v[152:155], v[226:229], v[14:17]
	v_mfma_f32_16x16x32_bf16 v[10:13], v[160:163], v[226:229], v[10:13]
	v_mfma_f32_16x16x32_bf16 v[54:57], v[164:167], v[184:187], v[54:57]
	v_mfma_f32_16x16x32_bf16 v[50:53], v[172:175], v[184:187], v[50:53]
	v_mfma_f32_16x16x32_bf16 v[38:41], v[164:167], v[196:199], v[38:41]
	v_mfma_f32_16x16x32_bf16 v[34:37], v[172:175], v[196:199], v[34:37]
	v_mfma_f32_16x16x32_bf16 v[22:25], v[164:167], v[214:217], v[22:25]
	v_mfma_f32_16x16x32_bf16 v[18:21], v[172:175], v[214:217], v[18:21]
	v_mfma_f32_16x16x32_bf16 v[6:9], v[164:167], v[222:225], v[6:9]
	v_mfma_f32_16x16x32_bf16 v[2:5], v[172:175], v[222:225], v[2:5]
	v_mfma_f32_16x16x32_bf16 v[54:57], v[168:171], v[188:191], v[54:57]
	v_mfma_f32_16x16x32_bf16 v[50:53], v[176:179], v[188:191], v[50:53]
	v_mfma_f32_16x16x32_bf16 v[38:41], v[168:171], v[210:213], v[38:41]
	v_mfma_f32_16x16x32_bf16 v[34:37], v[176:179], v[210:213], v[34:37]
	v_mfma_f32_16x16x32_bf16 v[22:25], v[168:171], v[218:221], v[22:25]
	v_mfma_f32_16x16x32_bf16 v[18:21], v[176:179], v[218:221], v[18:21]
	v_mfma_f32_16x16x32_bf16 v[6:9], v[168:171], v[226:229], v[6:9]
	v_mfma_f32_16x16x32_bf16 v[2:5], v[176:179], v[226:229], v[2:5]
	s_barrier
	s_add_i32 s24, s24, 2
	s_add_u32 s12, s12, 0x100
	s_addc_u32 s13, s13, 0
	s_add_u32 s19, s19, 0x100
	s_addc_u32 s21, s21, 0
	s_cmp_gt_u32 s24, 13
	s_cbranch_scc0 .LBB0_986
	s_setprio 0
	s_and_b64 vcc, exec, s[10:11]
	s_cbranch_vccz .LBB0_989
	s_barrier
